# LDS read rebalancing on the nt/reverse-order base: B fragment reads one phase early (phase-5 set in fp8+bf16 loops, phase-1 set in bf16 loops), counted vmcnt(10) before the covering barrier
# baseline (speedup 1.0000x reference)
; #define G_STAGE(bufoff, gbase, voff) do { _Pragma("unroll") for (int _i = 0; _i < 2; ++_i) \
;         __builtin_amdgcn_global_load_lds((const unsigned*)((const char*)(gbase) + (voff)[_i]), (LAS unsigned*)(lds + (bufoff) + ldsw + _i * 8192), 16, 0, 0); } while (0)
; #define G_WAIT_V(n) asm volatile("s_waitcnt vmcnt(" #n ")" ::: "memory")
; #define G_WAIT_L(n) asm volatile("s_waitcnt lgkmcnt(" #n ")" ::: "memory")
; #define G_BAR __builtin_amdgcn_s_barrier()
; #define G_SCHED __builtin_amdgcn_sched_barrier(0)
; template <int MODE  , class Epi, class Sched>
; __device__ __forceinline__ void gemm_phase(LAS unsigned char* lds, const GemmDesc g, const Sched& S, const Epi& E) {
;     ...
;             G_LDB(B0, 0, 0); G_SCHED; G_LDA(At, 0, 0); G_STAGE(G_SA(1, 1), a1 + hstepA, voffA);
;             G_WAIT_L(8); G_BAR; G_WAIT_L(0); G_MMA(0, 0, At, B0); G_BAR; G_SCHED;
;             G_LDB(B1, 0, 1); G_STAGE(G_SB(0, 0), b2, voffB);
;             G_BAR; G_WAIT_L(0); G_MMA(0, 1, At, B1); G_BAR;
;             G_LDA(At, 0, 1); G_STAGE(G_SA(0, 0), a2, voffA);
;             G_BAR; G_WAIT_L(0); G_MMA(1, 0, At, B0); G_BAR; G_SCHED;
;             G_STAGE(G_SB(0, 1), b2 + hstepB, voffB);
;             G_WAIT_V(6); G_BAR; G_MMA(1, 1, At, B1); G_BAR;
;             G_LDB(B0, 1, 0); G_SCHED; G_LDA(At, 1, 0); G_STAGE(G_SA(0, 1), a2 + hstepA, voffA);
.Lnodb_p1b:
.LBB0_737:
	ds_read_b128 v[2:5], v168
	ds_read_b128 v[6:9], v168 offset:1024
	ds_read_b128 v[10:13], v168 offset:2048
	ds_read_b128 v[14:17], v168 offset:3072
	s_add_u32 s46, s50, 0x100
	s_addc_u32 s47, s51, 0
	s_cmp_eq_u32 s79, 12
	s_cselect_b32 s55, s45, s47
	s_cselect_b32 s54, s44, s46
	s_cselect_b32 s53, s3, s78
	s_cselect_b32 s52, s2, s77
	s_add_u32 s98, s50, 0x44080
	s_addc_u32 s99, s51, 0
	s_add_i32 m0, s62, 0xc000
	ds_read_b128 v[174:177], v169
	ds_read_b128 v[178:181], v169 offset:1024
	ds_read_b128 v[182:185], v169 offset:2048
	ds_read_b128 v[186:189], v169 offset:3072
	ds_read_b128 v[192:195], v169 offset:4096
	ds_read_b128 v[196:199], v169 offset:5120
	ds_read_b128 v[200:203], v169 offset:6144
	ds_read_b128 v[204:207], v169 offset:7168
	global_load_lds_dwordx4 v152, s[98:99]
	s_add_i32 m0, s62, 0xe000
	s_nop 0
	global_load_lds_dwordx4 v148, s[98:99]
	s_waitcnt lgkmcnt(8)
	s_barrier
	s_waitcnt lgkmcnt(0)
	v_mfma_scale_f32_16x16x128_f8f6f4 v[142:145], v[2:9], v[174:181], v[142:145], v170, v170 op_sel_hi:[0,0,0]
	v_mfma_scale_f32_16x16x128_f8f6f4 v[138:141], v[10:17], v[174:181], v[138:141], v170, v170 op_sel_hi:[0,0,0]
	v_mfma_scale_f32_16x16x128_f8f6f4 v[126:129], v[2:9], v[182:189], v[126:129], v170, v170 op_sel_hi:[0,0,0]
	v_mfma_scale_f32_16x16x128_f8f6f4 v[122:125], v[10:17], v[182:189], v[122:125], v170, v170 op_sel_hi:[0,0,0]
	v_mfma_scale_f32_16x16x128_f8f6f4 v[110:113], v[2:9], v[192:199], v[110:113], v170, v170 op_sel_hi:[0,0,0]
	v_mfma_scale_f32_16x16x128_f8f6f4 v[106:109], v[10:17], v[192:199], v[106:109], v170, v170 op_sel_hi:[0,0,0]
	v_mfma_scale_f32_16x16x128_f8f6f4 v[94:97], v[2:9], v[200:207], v[94:97], v170, v170 op_sel_hi:[0,0,0]
	v_mfma_scale_f32_16x16x128_f8f6f4 v[90:93], v[10:17], v[200:207], v[90:93], v170, v170 op_sel_hi:[0,0,0]
	s_barrier
	s_add_i32 s0, s69, s60
	s_mov_b32 m0, s0
	ds_read_b128 v[208:211], v171
	ds_read_b128 v[212:215], v171 offset:1024
	ds_read_b128 v[216:219], v171 offset:2048
	ds_read_b128 v[220:223], v171 offset:3072
	global_load_lds_dwordx4 v150, s[52:53]
	s_add_i32 m0, s0, 0x2000
	s_nop 0
	global_load_lds_dwordx4 v146, s[52:53]
	s_barrier
	s_waitcnt lgkmcnt(0)
	v_mfma_scale_f32_16x16x128_f8f6f4 v[134:137], v[208:215], v[174:181], v[134:137], v170, v170 op_sel_hi:[0,0,0]
	v_mfma_scale_f32_16x16x128_f8f6f4 v[130:133], v[216:223], v[174:181], v[130:133], v170, v170 op_sel_hi:[0,0,0]
	v_mfma_scale_f32_16x16x128_f8f6f4 v[118:121], v[208:215], v[182:189], v[118:121], v170, v170 op_sel_hi:[0,0,0]
	v_mfma_scale_f32_16x16x128_f8f6f4 v[114:117], v[216:223], v[182:189], v[114:117], v170, v170 op_sel_hi:[0,0,0]
	v_mfma_scale_f32_16x16x128_f8f6f4 v[102:105], v[208:215], v[192:199], v[102:105], v170, v170 op_sel_hi:[0,0,0]
	v_mfma_scale_f32_16x16x128_f8f6f4 v[98:101], v[216:223], v[192:199], v[98:101], v170, v170 op_sel_hi:[0,0,0]
	v_mfma_scale_f32_16x16x128_f8f6f4 v[86:89], v[208:215], v[200:207], v[86:89], v170, v170 op_sel_hi:[0,0,0]
	v_mfma_scale_f32_16x16x128_f8f6f4 v[82:85], v[216:223], v[200:207], v[82:85], v170, v170 op_sel_hi:[0,0,0]
	s_mov_b32 m0, s62
	s_barrier
	ds_read_b128 v[174:177], v169 offset:16384
	ds_read_b128 v[178:181], v169 offset:17408
	ds_read_b128 v[182:185], v169 offset:18432
	ds_read_b128 v[186:189], v169 offset:19456
	ds_read_b128 v[192:195], v169 offset:20480
	ds_read_b128 v[196:199], v169 offset:21504
	ds_read_b128 v[200:203], v169 offset:22528
	ds_read_b128 v[204:207], v169 offset:23552
	global_load_lds_dwordx4 v152, s[54:55]
	s_mov_b32 m0, s63
	s_nop 0
	global_load_lds_dwordx4 v148, s[54:55]
	s_waitcnt vmcnt(10)
	s_barrier
	s_waitcnt lgkmcnt(0)
	v_mfma_scale_f32_16x16x128_f8f6f4 v[78:81], v[2:9], v[174:181], v[78:81], v170, v170 op_sel_hi:[0,0,0]
	v_mfma_scale_f32_16x16x128_f8f6f4 v[74:77], v[10:17], v[174:181], v[74:77], v170, v170 op_sel_hi:[0,0,0]
	v_mfma_scale_f32_16x16x128_f8f6f4 v[62:65], v[2:9], v[182:189], v[62:65], v170, v170 op_sel_hi:[0,0,0]
	v_mfma_scale_f32_16x16x128_f8f6f4 v[58:61], v[10:17], v[182:189], v[58:61], v170, v170 op_sel_hi:[0,0,0]
	v_mfma_scale_f32_16x16x128_f8f6f4 v[46:49], v[2:9], v[192:199], v[46:49], v170, v170 op_sel_hi:[0,0,0]
	v_mfma_scale_f32_16x16x128_f8f6f4 v[42:45], v[10:17], v[192:199], v[42:45], v170, v170 op_sel_hi:[0,0,0]
	v_mfma_scale_f32_16x16x128_f8f6f4 v[30:33], v[2:9], v[200:207], v[30:33], v170, v170 op_sel_hi:[0,0,0]
	v_mfma_scale_f32_16x16x128_f8f6f4 v[26:29], v[10:17], v[200:207], v[26:29], v170, v170 op_sel_hi:[0,0,0]
	s_barrier
	v_add_u32_e32 v14, 0x18000, v166
	ds_read_b128 v[2:5], v14
	ds_read_b128 v[6:9], v14 offset:1024
	ds_read_b128 v[10:13], v14 offset:2048
	ds_read_b128 v[14:17], v14 offset:3072
	s_add_u32 s0, s52, 0x44000
	s_addc_u32 s1, s53, 0
	s_add_i32 s10, s70, s60
	s_mov_b32 m0, s10
	s_nop 0
	global_load_lds_dwordx4 v150, s[0:1]
	s_add_i32 m0, s10, 0x2000
	s_nop 0
	global_load_lds_dwordx4 v146, s[0:1]
	s_waitcnt vmcnt(6)
	s_barrier
	v_mfma_scale_f32_16x16x128_f8f6f4 v[70:73], v[208:215], v[174:181], v[70:73], v170, v170 op_sel_hi:[0,0,0]
	v_mfma_scale_f32_16x16x128_f8f6f4 v[66:69], v[216:223], v[174:181], v[66:69], v170, v170 op_sel_hi:[0,0,0]
	v_mfma_scale_f32_16x16x128_f8f6f4 v[54:57], v[208:215], v[182:189], v[54:57], v170, v170 op_sel_hi:[0,0,0]
	v_mfma_scale_f32_16x16x128_f8f6f4 v[50:53], v[216:223], v[182:189], v[50:53], v170, v170 op_sel_hi:[0,0,0]
	v_mfma_scale_f32_16x16x128_f8f6f4 v[38:41], v[208:215], v[192:199], v[38:41], v170, v170 op_sel_hi:[0,0,0]
	v_mfma_scale_f32_16x16x128_f8f6f4 v[34:37], v[216:223], v[192:199], v[34:37], v170, v170 op_sel_hi:[0,0,0]
	v_mfma_scale_f32_16x16x128_f8f6f4 v[22:25], v[208:215], v[200:207], v[22:25], v170, v170 op_sel_hi:[0,0,0]
	v_mfma_scale_f32_16x16x128_f8f6f4 v[18:21], v[216:223], v[200:207], v[18:21], v170, v170 op_sel_hi:[0,0,0]
	s_add_i32 s10, 0, 0x18000
	s_barrier
; #define G_STAGE(bufoff, gbase, voff) do { _Pragma("unroll") for (int _i = 0; _i < 2; ++_i) \
;         __builtin_amdgcn_global_load_lds((const unsigned*)((const char*)(gbase) + (voff)[_i]), (LAS unsigned*)(lds + (bufoff) + ldsw + _i * 8192), 16, 0, 0); } while (0)
; #define G_WAIT_V(n) asm volatile("s_waitcnt vmcnt(" #n ")" ::: "memory")
; #define G_WAIT_L(n) asm volatile("s_waitcnt lgkmcnt(" #n ")" ::: "memory")
; #define G_BAR __builtin_amdgcn_s_barrier()
; #define G_SCHED __builtin_amdgcn_sched_barrier(0)
; template <int MODE  , class Epi, class Sched>
; __device__ __forceinline__ void gemm_phase(LAS unsigned char* lds, const GemmDesc g, const Sched& S, const Epi& E) {
;     ...
;             G_LDB(B0, 1, 0); G_SCHED; G_LDA(At, 1, 0); G_STAGE(G_SA(0, 1), a2 + hstepA, voffA);
;             G_WAIT_L(8); G_BAR; G_WAIT_L(0); G_MMA(0, 0, At, B0); G_BAR; G_SCHED;
;             G_LDB(B1, 1, 1); G_STAGE(G_SB(1, 0), b3, voffB);
;             G_BAR; G_WAIT_L(0); G_MMA(0, 1, At, B1); G_BAR;
;             G_LDA(At, 1, 1); G_STAGE(G_SA(1, 0), a3, voffA);
;             G_BAR; G_WAIT_L(0); G_MMA(1, 0, At, B0); G_BAR; G_SCHED;
;             G_STAGE(G_SB(1, 1), b3 + hstepB, voffB);
;             G_WAIT_V(6); G_BAR; G_MMA(1, 1, At, B1); G_BAR;
	s_add_u32 s0, s54, 0x44000
	s_addc_u32 s1, s55, 0
	s_mov_b32 m0, s64
	ds_read_b128 v[174:177], v169 offset:32768
	ds_read_b128 v[178:181], v169 offset:33792
	ds_read_b128 v[182:185], v169 offset:34816
	ds_read_b128 v[186:189], v169 offset:35840
	ds_read_b128 v[192:195], v169 offset:36864
	ds_read_b128 v[196:199], v169 offset:37888
	ds_read_b128 v[200:203], v169 offset:38912
	ds_read_b128 v[204:207], v169 offset:39936
	global_load_lds_dwordx4 v152, s[0:1]
	s_mov_b32 m0, s65
	s_nop 0
	global_load_lds_dwordx4 v148, s[0:1]
	s_waitcnt lgkmcnt(8)
	s_barrier
	s_waitcnt lgkmcnt(0)
	v_mfma_scale_f32_16x16x128_f8f6f4 v[142:145], v[2:9], v[174:181], v[142:145], v170, v170 op_sel_hi:[0,0,0]
	v_mfma_scale_f32_16x16x128_f8f6f4 v[138:141], v[10:17], v[174:181], v[138:141], v170, v170 op_sel_hi:[0,0,0]
	v_mfma_scale_f32_16x16x128_f8f6f4 v[126:129], v[2:9], v[182:189], v[126:129], v170, v170 op_sel_hi:[0,0,0]
	v_mfma_scale_f32_16x16x128_f8f6f4 v[122:125], v[10:17], v[182:189], v[122:125], v170, v170 op_sel_hi:[0,0,0]
	v_mfma_scale_f32_16x16x128_f8f6f4 v[110:113], v[2:9], v[192:199], v[110:113], v170, v170 op_sel_hi:[0,0,0]
	v_mfma_scale_f32_16x16x128_f8f6f4 v[106:109], v[10:17], v[192:199], v[106:109], v170, v170 op_sel_hi:[0,0,0]
	v_mfma_scale_f32_16x16x128_f8f6f4 v[94:97], v[2:9], v[200:207], v[94:97], v170, v170 op_sel_hi:[0,0,0]
	v_mfma_scale_f32_16x16x128_f8f6f4 v[90:93], v[10:17], v[200:207], v[90:93], v170, v170 op_sel_hi:[0,0,0]
	s_barrier
	s_add_i32 s11, 0, 0x1c000
	s_add_i32 s0, s10, s60
	v_add_u32_e32 v173, s11, v166
	s_add_u32 s98, s52, 0x80
	s_addc_u32 s99, s53, 0
	s_mov_b32 m0, s0
	ds_read_b128 v[208:211], v173
	ds_read_b128 v[212:215], v173 offset:1024
	ds_read_b128 v[216:219], v173 offset:2048
	ds_read_b128 v[220:223], v173 offset:3072
	global_load_lds_dwordx4 v150, s[98:99]
	s_add_i32 m0, s0, 0x2000
	s_nop 0
	global_load_lds_dwordx4 v146, s[98:99]
	s_barrier
	s_waitcnt lgkmcnt(0)
	v_mfma_scale_f32_16x16x128_f8f6f4 v[134:137], v[208:215], v[174:181], v[134:137], v170, v170 op_sel_hi:[0,0,0]
	v_mfma_scale_f32_16x16x128_f8f6f4 v[130:133], v[216:223], v[174:181], v[130:133], v170, v170 op_sel_hi:[0,0,0]
	v_mfma_scale_f32_16x16x128_f8f6f4 v[118:121], v[208:215], v[182:189], v[118:121], v170, v170 op_sel_hi:[0,0,0]
	v_mfma_scale_f32_16x16x128_f8f6f4 v[114:117], v[216:223], v[182:189], v[114:117], v170, v170 op_sel_hi:[0,0,0]
	v_mfma_scale_f32_16x16x128_f8f6f4 v[102:105], v[208:215], v[192:199], v[102:105], v170, v170 op_sel_hi:[0,0,0]
	v_mfma_scale_f32_16x16x128_f8f6f4 v[98:101], v[216:223], v[192:199], v[98:101], v170, v170 op_sel_hi:[0,0,0]
	v_mfma_scale_f32_16x16x128_f8f6f4 v[86:89], v[208:215], v[200:207], v[86:89], v170, v170 op_sel_hi:[0,0,0]
	v_mfma_scale_f32_16x16x128_f8f6f4 v[82:85], v[216:223], v[200:207], v[82:85], v170, v170 op_sel_hi:[0,0,0]
	s_mov_b32 m0, s67
	s_add_u32 s98, s54, 0x80
	s_addc_u32 s99, s55, 0
	s_barrier
	ds_read_b128 v[174:177], v169 offset:49152
	ds_read_b128 v[178:181], v169 offset:50176
	ds_read_b128 v[182:185], v169 offset:51200
	ds_read_b128 v[186:189], v169 offset:52224
	ds_read_b128 v[192:195], v169 offset:53248
	ds_read_b128 v[196:199], v169 offset:54272
	ds_read_b128 v[200:203], v169 offset:55296
	ds_read_b128 v[204:207], v169 offset:56320
	global_load_lds_dwordx4 v152, s[98:99]
	s_mov_b32 m0, s68
	s_nop 0
	global_load_lds_dwordx4 v148, s[98:99]
	s_barrier
	s_waitcnt lgkmcnt(0)
	v_mfma_scale_f32_16x16x128_f8f6f4 v[78:81], v[2:9], v[174:181], v[78:81], v170, v170 op_sel_hi:[0,0,0]
	v_mfma_scale_f32_16x16x128_f8f6f4 v[74:77], v[10:17], v[174:181], v[74:77], v170, v170 op_sel_hi:[0,0,0]
	v_mfma_scale_f32_16x16x128_f8f6f4 v[62:65], v[2:9], v[182:189], v[62:65], v170, v170 op_sel_hi:[0,0,0]
	v_mfma_scale_f32_16x16x128_f8f6f4 v[58:61], v[10:17], v[182:189], v[58:61], v170, v170 op_sel_hi:[0,0,0]
	v_mfma_scale_f32_16x16x128_f8f6f4 v[46:49], v[2:9], v[192:199], v[46:49], v170, v170 op_sel_hi:[0,0,0]
	v_mfma_scale_f32_16x16x128_f8f6f4 v[42:45], v[10:17], v[192:199], v[42:45], v170, v170 op_sel_hi:[0,0,0]
	v_mfma_scale_f32_16x16x128_f8f6f4 v[30:33], v[2:9], v[200:207], v[30:33], v170, v170 op_sel_hi:[0,0,0]
	v_mfma_scale_f32_16x16x128_f8f6f4 v[26:29], v[10:17], v[200:207], v[26:29], v170, v170 op_sel_hi:[0,0,0]
	s_barrier
	s_add_u32 s0, s52, 0x44080
	s_addc_u32 s1, s53, 0
	s_add_i32 s10, s11, s60
	s_mov_b32 m0, s10
	s_nop 0
	global_load_lds_dwordx4 v150, s[0:1]
	s_add_i32 m0, s10, 0x2000
	s_nop 0
	global_load_lds_dwordx4 v146, s[0:1]
	s_waitcnt vmcnt(6)
	s_barrier
	v_mfma_scale_f32_16x16x128_f8f6f4 v[70:73], v[208:215], v[174:181], v[70:73], v170, v170 op_sel_hi:[0,0,0]
	s_add_i32 s79, s79, 2
	s_add_u32 s77, s77, 0x100
	s_addc_u32 s78, s78, 0
	s_cmp_gt_u32 s79, 13
	s_mov_b64 s[50:51], s[46:47]
	v_mfma_scale_f32_16x16x128_f8f6f4 v[66:69], v[216:223], v[174:181], v[66:69], v170, v170 op_sel_hi:[0,0,0]
	v_mfma_scale_f32_16x16x128_f8f6f4 v[54:57], v[208:215], v[182:189], v[54:57], v170, v170 op_sel_hi:[0,0,0]
	v_mfma_scale_f32_16x16x128_f8f6f4 v[50:53], v[216:223], v[182:189], v[50:53], v170, v170 op_sel_hi:[0,0,0]
	v_mfma_scale_f32_16x16x128_f8f6f4 v[38:41], v[208:215], v[192:199], v[38:41], v170, v170 op_sel_hi:[0,0,0]
	v_mfma_scale_f32_16x16x128_f8f6f4 v[34:37], v[216:223], v[192:199], v[34:37], v170, v170 op_sel_hi:[0,0,0]
	v_mfma_scale_f32_16x16x128_f8f6f4 v[22:25], v[208:215], v[200:207], v[22:25], v170, v170 op_sel_hi:[0,0,0]
	v_mfma_scale_f32_16x16x128_f8f6f4 v[18:21], v[216:223], v[200:207], v[18:21], v170, v170 op_sel_hi:[0,0,0]
	s_cbranch_scc1 .Lkdone_p1b
	s_barrier
	s_branch .LBB0_737

; #define G_STAGE(bufoff, gbase, voff) do { _Pragma("unroll") for (int _i = 0; _i < 2; ++_i) \
;         __builtin_amdgcn_global_load_lds((const unsigned*)((const char*)(gbase) + (voff)[_i]), (LAS unsigned*)(lds + (bufoff) + ldsw + _i * 8192), 16, 0, 0); } while (0)
; #define G_WAIT_V(n) asm volatile("s_waitcnt vmcnt(" #n ")" ::: "memory")
; #define G_WAIT_L(n) asm volatile("s_waitcnt lgkmcnt(" #n ")" ::: "memory")
; #define G_BAR __builtin_amdgcn_s_barrier()
; #define G_SCHED __builtin_amdgcn_sched_barrier(0)
; template <int MODE  , class Epi, class Sched>
; __device__ __forceinline__ void gemm_phase(LAS unsigned char* lds, const GemmDesc g, const Sched& S, const Epi& E) {
;     ...
;             G_LDB(B0, 0, 0); G_SCHED; G_LDA(At, 0, 0); G_STAGE(G_SA(1, 1), a1 + hstepA, voffA);
;             G_WAIT_L(8); G_BAR; G_WAIT_L(0); G_MMA(0, 0, At, B0); G_BAR; G_SCHED;
;             G_LDB(B1, 0, 1); G_STAGE(G_SB(0, 0), b2, voffB);
;             G_BAR; G_WAIT_L(0); G_MMA(0, 1, At, B1); G_BAR;
;             G_LDA(At, 0, 1); G_STAGE(G_SA(0, 0), a2, voffA);
;             G_BAR; G_WAIT_L(0); G_MMA(1, 0, At, B0); G_BAR; G_SCHED;
;             G_STAGE(G_SB(0, 1), b2 + hstepB, voffB);
;             G_WAIT_V(6); G_BAR; G_MMA(1, 1, At, B1); G_BAR;
;             G_LDB(B0, 1, 0); G_SCHED; G_LDA(At, 1, 0); G_STAGE(G_SA(0, 1), a2 + hstepA, voffA);
.LBB0_815:
	s_add_u32 s44, s42, 0x100
	s_addc_u32 s45, s43, 0
	s_cmp_eq_u32 s68, 12
	s_cselect_b32 s49, s35, s45
	s_cselect_b32 s48, s34, s44
	s_cselect_b32 s47, s3, s67
	s_cselect_b32 s46, s2, s21
	s_add_u32 s98, s42, 0x84080
	s_addc_u32 s99, s43, 0
	s_add_i32 m0, s52, 0xc000
	ds_read_b128 v[158:161], v174
	ds_read_b128 v[162:165], v174 offset:1024
	ds_read_b128 v[166:169], v174 offset:2048
	ds_read_b128 v[176:179], v174 offset:3072
	ds_read_b128 v[180:183], v174 offset:4096
	ds_read_b128 v[184:187], v174 offset:5120
	ds_read_b128 v[192:195], v174 offset:6144
	ds_read_b128 v[196:199], v174 offset:7168
	global_load_lds_dwordx4 v146, s[98:99]
	s_add_i32 m0, s52, 0xe000
	s_nop 0
	global_load_lds_dwordx4 v150, s[98:99]
	s_waitcnt lgkmcnt(8)
	s_barrier
	s_waitcnt lgkmcnt(0)
	v_mfma_f32_16x16x32_bf16 v[126:129], v[232:235], v[158:161], v[126:129]
	v_mfma_f32_16x16x32_bf16 v[122:125], v[240:243], v[158:161], v[122:125]
	v_mfma_f32_16x16x32_bf16 v[118:121], v[232:235], v[166:169], v[118:121]
	v_mfma_f32_16x16x32_bf16 v[114:117], v[240:243], v[166:169], v[114:117]
	v_mfma_f32_16x16x32_bf16 v[110:113], v[232:235], v[180:183], v[110:113]
	v_mfma_f32_16x16x32_bf16 v[106:109], v[240:243], v[180:183], v[106:109]
	v_mfma_f32_16x16x32_bf16 v[102:105], v[232:235], v[192:195], v[102:105]
	v_mfma_f32_16x16x32_bf16 v[98:101], v[240:243], v[192:195], v[98:101]
	v_mfma_f32_16x16x32_bf16 v[126:129], v[236:239], v[162:165], v[126:129]
	v_mfma_f32_16x16x32_bf16 v[122:125], v[244:247], v[162:165], v[122:125]
	v_mfma_f32_16x16x32_bf16 v[118:121], v[236:239], v[176:179], v[118:121]
	v_mfma_f32_16x16x32_bf16 v[114:117], v[244:247], v[176:179], v[114:117]
	v_mfma_f32_16x16x32_bf16 v[110:113], v[236:239], v[184:187], v[110:113]
	v_mfma_f32_16x16x32_bf16 v[106:109], v[244:247], v[184:187], v[106:109]
	v_mfma_f32_16x16x32_bf16 v[102:105], v[236:239], v[196:199], v[102:105]
	v_mfma_f32_16x16x32_bf16 v[98:101], v[244:247], v[196:199], v[98:101]
	s_barrier
	v_add_u32_e32 v170, s59, v172
	s_add_i32 s0, s58, s51
	ds_read_b128 v[200:203], v170
	ds_read_b128 v[204:207], v170 offset:1024
	ds_read_b128 v[208:211], v170 offset:2048
	ds_read_b128 v[212:215], v170 offset:3072
	s_mov_b32 m0, s0
	s_nop 0
	global_load_lds_dwordx4 v148, s[46:47]
	s_add_i32 m0, s0, 0x2000
	s_nop 0
	global_load_lds_dwordx4 v152, s[46:47]
	s_barrier
	s_waitcnt lgkmcnt(0)
	v_mfma_f32_16x16x32_bf16 v[94:97], v[200:203], v[158:161], v[94:97]
	v_mfma_f32_16x16x32_bf16 v[90:93], v[208:211], v[158:161], v[90:93]
	v_mfma_f32_16x16x32_bf16 v[86:89], v[200:203], v[166:169], v[86:89]
	v_mfma_f32_16x16x32_bf16 v[82:85], v[208:211], v[166:169], v[82:85]
	v_mfma_f32_16x16x32_bf16 v[78:81], v[200:203], v[180:183], v[78:81]
	v_mfma_f32_16x16x32_bf16 v[74:77], v[208:211], v[180:183], v[74:77]
	v_mfma_f32_16x16x32_bf16 v[70:73], v[200:203], v[192:195], v[70:73]
	v_mfma_f32_16x16x32_bf16 v[66:69], v[208:211], v[192:195], v[66:69]
	v_mfma_f32_16x16x32_bf16 v[94:97], v[204:207], v[162:165], v[94:97]
	v_mfma_f32_16x16x32_bf16 v[90:93], v[212:215], v[162:165], v[90:93]
	v_mfma_f32_16x16x32_bf16 v[86:89], v[204:207], v[176:179], v[86:89]
	v_mfma_f32_16x16x32_bf16 v[82:85], v[212:215], v[176:179], v[82:85]
	v_mfma_f32_16x16x32_bf16 v[78:81], v[204:207], v[184:187], v[78:81]
	v_mfma_f32_16x16x32_bf16 v[74:77], v[212:215], v[184:187], v[74:77]
	v_mfma_f32_16x16x32_bf16 v[70:73], v[204:207], v[196:199], v[70:73]
	v_mfma_f32_16x16x32_bf16 v[66:69], v[212:215], v[196:199], v[66:69]
	s_mov_b32 m0, s52
	s_barrier
	ds_read_b128 v[158:161], v174 offset:16384
	ds_read_b128 v[162:165], v174 offset:17408
	ds_read_b128 v[166:169], v174 offset:18432
	ds_read_b128 v[176:179], v174 offset:19456
	ds_read_b128 v[180:183], v174 offset:20480
	ds_read_b128 v[184:187], v174 offset:21504
	ds_read_b128 v[192:195], v174 offset:22528
	ds_read_b128 v[196:199], v174 offset:23552
	global_load_lds_dwordx4 v146, s[48:49]
	s_mov_b32 m0, s53
	s_nop 0
	global_load_lds_dwordx4 v150, s[48:49]
	s_waitcnt vmcnt(10)
	s_barrier
	s_waitcnt lgkmcnt(0)
	v_mfma_f32_16x16x32_bf16 v[62:65], v[232:235], v[158:161], v[62:65]
	v_mfma_f32_16x16x32_bf16 v[58:61], v[240:243], v[158:161], v[58:61]
	v_mfma_f32_16x16x32_bf16 v[54:57], v[232:235], v[166:169], v[54:57]
	v_mfma_f32_16x16x32_bf16 v[50:53], v[240:243], v[166:169], v[50:53]
	v_mfma_f32_16x16x32_bf16 v[46:49], v[232:235], v[180:183], v[46:49]
	v_mfma_f32_16x16x32_bf16 v[42:45], v[240:243], v[180:183], v[42:45]
	v_mfma_f32_16x16x32_bf16 v[38:41], v[232:235], v[192:195], v[38:41]
	v_mfma_f32_16x16x32_bf16 v[34:37], v[240:243], v[192:195], v[34:37]
	v_mfma_f32_16x16x32_bf16 v[62:65], v[236:239], v[162:165], v[62:65]
	v_mfma_f32_16x16x32_bf16 v[58:61], v[244:247], v[162:165], v[58:61]
	v_mfma_f32_16x16x32_bf16 v[54:57], v[236:239], v[176:179], v[54:57]
	v_mfma_f32_16x16x32_bf16 v[50:53], v[244:247], v[176:179], v[50:53]
	v_mfma_f32_16x16x32_bf16 v[46:49], v[236:239], v[184:187], v[46:49]
	v_mfma_f32_16x16x32_bf16 v[42:45], v[244:247], v[184:187], v[42:45]
	v_mfma_f32_16x16x32_bf16 v[38:41], v[236:239], v[196:199], v[38:41]
	v_mfma_f32_16x16x32_bf16 v[34:37], v[244:247], v[196:199], v[34:37]
	s_barrier
	v_add_u32_e32 v142, 0x18000, v172
	ds_read_b128 v[130:133], v142
	ds_read_b128 v[134:137], v142 offset:1024
	ds_read_b128 v[138:141], v142 offset:2048
	ds_read_b128 v[142:145], v142 offset:3072
	s_add_u32 s0, s46, 0x84000
	s_addc_u32 s1, s47, 0
	s_add_i32 s10, s59, s51
	s_mov_b32 m0, s10
	s_nop 0
	global_load_lds_dwordx4 v148, s[0:1]
	s_add_i32 m0, s10, 0x2000
	s_nop 0
	global_load_lds_dwordx4 v152, s[0:1]
	s_waitcnt vmcnt(6)
	s_barrier
; #define G_STAGE(bufoff, gbase, voff) do { _Pragma("unroll") for (int _i = 0; _i < 2; ++_i) \
;         __builtin_amdgcn_global_load_lds((const unsigned*)((const char*)(gbase) + (voff)[_i]), (LAS unsigned*)(lds + (bufoff) + ldsw + _i * 8192), 16, 0, 0); } while (0)
; #define G_WAIT_V(n) asm volatile("s_waitcnt vmcnt(" #n ")" ::: "memory")
; #define G_WAIT_L(n) asm volatile("s_waitcnt lgkmcnt(" #n ")" ::: "memory")
; #define G_BAR __builtin_amdgcn_s_barrier()
; #define G_SCHED __builtin_amdgcn_sched_barrier(0)
; template <int MODE  , class Epi, class Sched>
; __device__ __forceinline__ void gemm_phase(LAS unsigned char* lds, const GemmDesc g, const Sched& S, const Epi& E) {
;     ...
;             G_WAIT_V(6); G_BAR; G_MMA(1, 1, At, B1); G_BAR;
;             G_LDB(B0, 1, 0); G_SCHED; G_LDA(At, 1, 0); G_STAGE(G_SA(0, 1), a2 + hstepA, voffA);
;             G_WAIT_L(8); G_BAR; G_WAIT_L(0); G_MMA(0, 0, At, B0); G_BAR; G_SCHED;
;             G_LDB(B1, 1, 1); G_STAGE(G_SB(1, 0), b3, voffB);
;             G_BAR; G_WAIT_L(0); G_MMA(0, 1, At, B1); G_BAR;
;             G_LDA(At, 1, 1); G_STAGE(G_SA(1, 0), a3, voffA);
;             G_BAR; G_WAIT_L(0); G_MMA(1, 0, At, B0); G_BAR; G_SCHED;
	v_mfma_f32_16x16x32_bf16 v[30:33], v[200:203], v[158:161], v[30:33]
	v_mfma_f32_16x16x32_bf16 v[26:29], v[208:211], v[158:161], v[26:29]
	v_mfma_f32_16x16x32_bf16 v[22:25], v[200:203], v[166:169], v[22:25]
	v_mfma_f32_16x16x32_bf16 v[18:21], v[208:211], v[166:169], v[18:21]
	v_mfma_f32_16x16x32_bf16 v[14:17], v[200:203], v[180:183], v[14:17]
	v_mfma_f32_16x16x32_bf16 v[10:13], v[208:211], v[180:183], v[10:13]
	v_mfma_f32_16x16x32_bf16 v[6:9], v[200:203], v[192:195], v[6:9]
	v_mfma_f32_16x16x32_bf16 v[2:5], v[208:211], v[192:195], v[2:5]
	v_mfma_f32_16x16x32_bf16 v[30:33], v[204:207], v[162:165], v[30:33]
	v_mfma_f32_16x16x32_bf16 v[26:29], v[212:215], v[162:165], v[26:29]
	v_mfma_f32_16x16x32_bf16 v[22:25], v[204:207], v[176:179], v[22:25]
	v_mfma_f32_16x16x32_bf16 v[18:21], v[212:215], v[176:179], v[18:21]
	v_mfma_f32_16x16x32_bf16 v[14:17], v[204:207], v[184:187], v[14:17]
	v_mfma_f32_16x16x32_bf16 v[10:13], v[212:215], v[184:187], v[10:13]
	v_mfma_f32_16x16x32_bf16 v[6:9], v[204:207], v[196:199], v[6:9]
	v_mfma_f32_16x16x32_bf16 v[2:5], v[212:215], v[196:199], v[2:5]
	s_add_i32 s10, 0, 0x18000
	s_barrier
	s_add_u32 s0, s48, 0x84000
	s_addc_u32 s1, s49, 0
	s_mov_b32 m0, s54
	ds_read_b128 v[158:161], v174 offset:32768
	ds_read_b128 v[162:165], v174 offset:33792
	ds_read_b128 v[166:169], v174 offset:34816
	ds_read_b128 v[176:179], v174 offset:35840
	ds_read_b128 v[180:183], v174 offset:36864
	ds_read_b128 v[184:187], v174 offset:37888
	ds_read_b128 v[192:195], v174 offset:38912
	ds_read_b128 v[196:199], v174 offset:39936
	global_load_lds_dwordx4 v146, s[0:1]
	s_mov_b32 m0, s55
	s_nop 0
	global_load_lds_dwordx4 v150, s[0:1]
	s_waitcnt lgkmcnt(8)
	s_barrier
	s_waitcnt lgkmcnt(0)
	v_mfma_f32_16x16x32_bf16 v[126:129], v[130:133], v[158:161], v[126:129]
	v_mfma_f32_16x16x32_bf16 v[122:125], v[138:141], v[158:161], v[122:125]
	v_mfma_f32_16x16x32_bf16 v[118:121], v[130:133], v[166:169], v[118:121]
	v_mfma_f32_16x16x32_bf16 v[114:117], v[138:141], v[166:169], v[114:117]
	v_mfma_f32_16x16x32_bf16 v[110:113], v[130:133], v[180:183], v[110:113]
	v_mfma_f32_16x16x32_bf16 v[106:109], v[138:141], v[180:183], v[106:109]
	v_mfma_f32_16x16x32_bf16 v[102:105], v[130:133], v[192:195], v[102:105]
	v_mfma_f32_16x16x32_bf16 v[98:101], v[138:141], v[192:195], v[98:101]
	v_mfma_f32_16x16x32_bf16 v[126:129], v[134:137], v[162:165], v[126:129]
	v_mfma_f32_16x16x32_bf16 v[122:125], v[142:145], v[162:165], v[122:125]
	v_mfma_f32_16x16x32_bf16 v[118:121], v[134:137], v[176:179], v[118:121]
	v_mfma_f32_16x16x32_bf16 v[114:117], v[142:145], v[176:179], v[114:117]
	v_mfma_f32_16x16x32_bf16 v[110:113], v[134:137], v[184:187], v[110:113]
	v_mfma_f32_16x16x32_bf16 v[106:109], v[142:145], v[184:187], v[106:109]
	v_mfma_f32_16x16x32_bf16 v[102:105], v[134:137], v[196:199], v[102:105]
	v_mfma_f32_16x16x32_bf16 v[98:101], v[142:145], v[196:199], v[98:101]
	s_barrier
	s_add_i32 s11, 0, 0x1c000
	s_add_i32 s0, s10, s51
	v_add_u32_e32 v175, s11, v172
	s_add_u32 s98, s46, 0x80
	s_addc_u32 s99, s47, 0
	s_mov_b32 m0, s0
	ds_read_b128 v[200:203], v175
	ds_read_b128 v[204:207], v175 offset:1024
	ds_read_b128 v[208:211], v175 offset:2048
	ds_read_b128 v[212:215], v175 offset:3072
	global_load_lds_dwordx4 v148, s[98:99]
	s_add_i32 m0, s0, 0x2000
	s_nop 0
	global_load_lds_dwordx4 v152, s[98:99]
	s_barrier
	s_waitcnt lgkmcnt(0)
	v_mfma_f32_16x16x32_bf16 v[94:97], v[200:203], v[158:161], v[94:97]
	v_mfma_f32_16x16x32_bf16 v[90:93], v[208:211], v[158:161], v[90:93]
	v_mfma_f32_16x16x32_bf16 v[86:89], v[200:203], v[166:169], v[86:89]
	v_mfma_f32_16x16x32_bf16 v[82:85], v[208:211], v[166:169], v[82:85]
	v_mfma_f32_16x16x32_bf16 v[78:81], v[200:203], v[180:183], v[78:81]
	v_mfma_f32_16x16x32_bf16 v[74:77], v[208:211], v[180:183], v[74:77]
	v_mfma_f32_16x16x32_bf16 v[70:73], v[200:203], v[192:195], v[70:73]
	v_mfma_f32_16x16x32_bf16 v[66:69], v[208:211], v[192:195], v[66:69]
	v_mfma_f32_16x16x32_bf16 v[94:97], v[204:207], v[162:165], v[94:97]
	v_mfma_f32_16x16x32_bf16 v[90:93], v[212:215], v[162:165], v[90:93]
	v_mfma_f32_16x16x32_bf16 v[86:89], v[204:207], v[176:179], v[86:89]
	v_mfma_f32_16x16x32_bf16 v[82:85], v[212:215], v[176:179], v[82:85]
	v_mfma_f32_16x16x32_bf16 v[78:81], v[204:207], v[184:187], v[78:81]
	v_mfma_f32_16x16x32_bf16 v[74:77], v[212:215], v[184:187], v[74:77]
	v_mfma_f32_16x16x32_bf16 v[70:73], v[204:207], v[196:199], v[70:73]
	v_mfma_f32_16x16x32_bf16 v[66:69], v[212:215], v[196:199], v[66:69]
	s_mov_b32 m0, s56
	s_add_u32 s98, s48, 0x80
	s_addc_u32 s99, s49, 0
	s_barrier
; #define G_STAGE(bufoff, gbase, voff) do { _Pragma("unroll") for (int _i = 0; _i < 2; ++_i) \
;         __builtin_amdgcn_global_load_lds((const unsigned*)((const char*)(gbase) + (voff)[_i]), (LAS unsigned*)(lds + (bufoff) + ldsw + _i * 8192), 16, 0, 0); } while (0)
; #define G_WAIT_V(n) asm volatile("s_waitcnt vmcnt(" #n ")" ::: "memory")
; #define G_WAIT_L(n) asm volatile("s_waitcnt lgkmcnt(" #n ")" ::: "memory")
; #define G_BAR __builtin_amdgcn_s_barrier()
; #define G_SCHED __builtin_amdgcn_sched_barrier(0)
; template <int MODE  , class Epi, class Sched>
; __device__ __forceinline__ void gemm_phase(LAS unsigned char* lds, const GemmDesc g, const Sched& S, const Epi& E) {
;     ...
;             G_LDA(At, 1, 1); G_STAGE(G_SA(1, 0), a3, voffA);
;             G_BAR; G_WAIT_L(0); G_MMA(1, 0, At, B0); G_BAR; G_SCHED;
;             G_STAGE(G_SB(1, 1), b3 + hstepB, voffB);
;             G_WAIT_V(6); G_BAR; G_MMA(1, 1, At, B1); G_BAR;
;         }
	ds_read_b128 v[158:161], v174 offset:49152
	ds_read_b128 v[162:165], v174 offset:50176
	ds_read_b128 v[166:169], v174 offset:51200
	ds_read_b128 v[176:179], v174 offset:52224
	ds_read_b128 v[180:183], v174 offset:53248
	ds_read_b128 v[184:187], v174 offset:54272
	ds_read_b128 v[192:195], v174 offset:55296
	ds_read_b128 v[196:199], v174 offset:56320
	global_load_lds_dwordx4 v146, s[98:99]
	s_mov_b32 m0, s57
	s_nop 0
	global_load_lds_dwordx4 v150, s[98:99]
	s_waitcnt vmcnt(10)
	s_barrier
	s_waitcnt lgkmcnt(0)
	v_mfma_f32_16x16x32_bf16 v[62:65], v[130:133], v[158:161], v[62:65]
	v_mfma_f32_16x16x32_bf16 v[58:61], v[138:141], v[158:161], v[58:61]
	v_mfma_f32_16x16x32_bf16 v[54:57], v[130:133], v[166:169], v[54:57]
	v_mfma_f32_16x16x32_bf16 v[50:53], v[138:141], v[166:169], v[50:53]
	v_mfma_f32_16x16x32_bf16 v[46:49], v[130:133], v[180:183], v[46:49]
	v_mfma_f32_16x16x32_bf16 v[42:45], v[138:141], v[180:183], v[42:45]
	v_mfma_f32_16x16x32_bf16 v[38:41], v[130:133], v[192:195], v[38:41]
	v_mfma_f32_16x16x32_bf16 v[34:37], v[138:141], v[192:195], v[34:37]
	v_mfma_f32_16x16x32_bf16 v[62:65], v[134:137], v[162:165], v[62:65]
	v_mfma_f32_16x16x32_bf16 v[58:61], v[142:145], v[162:165], v[58:61]
	v_mfma_f32_16x16x32_bf16 v[54:57], v[134:137], v[176:179], v[54:57]
	v_mfma_f32_16x16x32_bf16 v[50:53], v[142:145], v[176:179], v[50:53]
	v_mfma_f32_16x16x32_bf16 v[46:49], v[134:137], v[184:187], v[46:49]
	v_mfma_f32_16x16x32_bf16 v[42:45], v[142:145], v[184:187], v[42:45]
	v_mfma_f32_16x16x32_bf16 v[38:41], v[134:137], v[196:199], v[38:41]
	v_mfma_f32_16x16x32_bf16 v[34:37], v[142:145], v[196:199], v[34:37]
	s_barrier
	v_add_u32_e32 v244, s58, v172
	ds_read_b128 v[232:235], v244
	ds_read_b128 v[236:239], v244 offset:1024
	ds_read_b128 v[240:243], v244 offset:2048
	ds_read_b128 v[244:247], v244 offset:3072
	s_add_u32 s0, s46, 0x84080
	s_addc_u32 s1, s47, 0
	s_add_i32 s10, s11, s51
	s_mov_b32 m0, s10
	s_nop 0
	global_load_lds_dwordx4 v148, s[0:1]
	s_add_i32 m0, s10, 0x2000
	s_nop 0
	global_load_lds_dwordx4 v152, s[0:1]
	s_waitcnt vmcnt(6)
	s_barrier
	v_mfma_f32_16x16x32_bf16 v[30:33], v[200:203], v[158:161], v[30:33]
	s_add_i32 s68, s68, 2
	s_add_u32 s21, s21, 0x100
	s_addc_u32 s67, s67, 0
	s_cmp_gt_u32 s68, 13
	s_mov_b64 s[42:43], s[44:45]
	v_mfma_f32_16x16x32_bf16 v[26:29], v[208:211], v[158:161], v[26:29]
	v_mfma_f32_16x16x32_bf16 v[22:25], v[200:203], v[166:169], v[22:25]
	v_mfma_f32_16x16x32_bf16 v[18:21], v[208:211], v[166:169], v[18:21]
	v_mfma_f32_16x16x32_bf16 v[14:17], v[200:203], v[180:183], v[14:17]
	v_mfma_f32_16x16x32_bf16 v[10:13], v[208:211], v[180:183], v[10:13]
	v_mfma_f32_16x16x32_bf16 v[6:9], v[200:203], v[192:195], v[6:9]
	v_mfma_f32_16x16x32_bf16 v[2:5], v[208:211], v[192:195], v[2:5]
	v_mfma_f32_16x16x32_bf16 v[30:33], v[204:207], v[162:165], v[30:33]
	v_mfma_f32_16x16x32_bf16 v[26:29], v[212:215], v[162:165], v[26:29]
	v_mfma_f32_16x16x32_bf16 v[22:25], v[204:207], v[176:179], v[22:25]
	v_mfma_f32_16x16x32_bf16 v[18:21], v[212:215], v[176:179], v[18:21]
	v_mfma_f32_16x16x32_bf16 v[14:17], v[204:207], v[184:187], v[14:17]
	v_mfma_f32_16x16x32_bf16 v[10:13], v[212:215], v[184:187], v[10:13]
	v_mfma_f32_16x16x32_bf16 v[6:9], v[204:207], v[196:199], v[6:9]
	v_mfma_f32_16x16x32_bf16 v[2:5], v[212:215], v[196:199], v[2:5]
	s_cbranch_scc1 .Lkdone_sa
	s_barrier
	s_branch .LBB0_815

; __device__ __forceinline__ float bf_lo(unsigned w) { return __uint_as_float(w << 16); }
; __device__ __forceinline__ float bf_hi(unsigned w) { return __uint_as_float(w & 0xffff0000u); }
;     __device__ __forceinline__ bool operator()(f32x4 (&acc)[2][2][4][2], const Unit& u, int wr, int wc, int fr, int fq) const {
;         const int r0 = u.pm * BM + wr * 64 + fr, c0 = u.pn * BM + wc * 32 + fq * 8;
;         const bf16_t* S = u.kh ? SGB : SGR;
; #pragma unroll
;         for (int ai = 0; ai < 2; ++ai)
; #pragma unroll
;             for (int m = 0; m < 4; ++m) { const size_t off = (size_t)(r0 + ai * HALF + m * 16) * D + c0;
; #pragma unroll
;                 for (int bj = 0; bj < 2; ++bj) { const u32x4 s = *(const u32x4*)(S + off + bj * HALF);
;                     f32x4 v0 = acc[ai][bj][m][0], v1 = acc[ai][bj][m][1];
;                     v0[0] *= bf_lo(s.x); v0[1] *= bf_hi(s.x); v0[2] *= bf_lo(s.y); v0[3] *= bf_hi(s.y);
;                     v1[0] *= bf_lo(s.z); v1[1] *= bf_hi(s.z); v1[2] *= bf_lo(s.w); v1[3] *= bf_hi(s.w);
;                     acc[ai][bj][m][0] = v0; acc[ai][bj][m][1] = v1; } }
;     __device__ __forceinline__ bool operator()(f32x4 (&acc)[2][2][4][2], const Unit& u, int wr, int wc, int fr, int fq) const {
;         if (u.type == 0) return d(acc, u, wr, wc, fr, fq);
.Lkepi_sa:
	s_waitcnt lgkmcnt(0)
	s_cmp_lg_u32 s65, 0
	s_cselect_b64 s[42:43], -1, 0
	s_cmp_eq_u32 s65, 0
	s_cselect_b64 s[0:1], -1, 0
	s_and_b64 vcc, s[0:1], exec
	v_lshl_add_u32 v160, s64, 8, v1
	v_lshl_or_b32 v158, s66, 8, v173
	s_cselect_b32 s0, s5, s15
	s_cselect_b32 s1, s4, s14
	v_mov_b32_e32 v130, s1
	v_mov_b32_e32 v131, s0
	v_ashrrev_i32_e32 v159, 31, v158
	v_ashrrev_i32_e32 v161, 31, v160
	v_lshl_add_u64 v[170:171], v[158:159], 1, v[130:131]
	v_lshlrev_b64 v[130:131], 12, v[160:161]
	v_or_b32_e32 v162, 16, v160
	v_lshl_add_u64 v[130:131], v[170:171], 0, v[130:131]
	v_ashrrev_i32_e32 v163, 31, v162
	v_mov_b64_e32 v[228:229], v[130:131]
	global_load_dwordx4 v[142:145], v[130:131], off nt
	global_load_dwordx4 v[176:179], v[130:131], off offset:256 nt
	v_lshlrev_b64 v[130:131], 12, v[162:163]
	v_or_b32_e32 v164, 32, v160
	v_lshl_add_u64 v[130:131], v[170:171], 0, v[130:131]
	v_ashrrev_i32_e32 v165, 31, v164
	global_load_dwordx4 v[180:183], v[130:131], off nt
	global_load_dwordx4 v[184:187], v[130:131], off offset:256 nt
	v_lshlrev_b64 v[130:131], 12, v[164:165]
	v_lshl_add_u64 v[130:131], v[170:171], 0, v[130:131]
	global_load_dwordx4 v[192:195], v[130:131], off nt
	global_load_dwordx4 v[196:199], v[130:131], off offset:256 nt
	v_or_b32_e32 v166, 48, v160
	v_add_u32_e32 v168, 0x80, v160
	v_ashrrev_i32_e32 v167, 31, v166
	v_ashrrev_i32_e32 v169, 31, v168
	v_lshlrev_b64 v[130:131], 12, v[166:167]
	v_lshlrev_b64 v[132:133], 12, v[168:169]
	v_lshl_add_u64 v[130:131], v[170:171], 0, v[130:131]
	v_lshl_add_u64 v[134:135], v[170:171], 0, v[132:133]
	global_load_dwordx4 v[200:203], v[130:131], off nt
	global_load_dwordx4 v[138:141], v[130:131], off offset:256 nt
	s_nop 0
	global_load_dwordx4 v[130:133], v[134:135], off nt
	s_nop 0
	global_load_dwordx4 v[134:137], v[134:135], off offset:256 nt
	s_mov_b64 s[0:1], 0x90000
	v_lshl_add_u64 v[226:227], v[228:229], 0, s[0:1]
	global_load_dwordx4 v[232:235], v[226:227], off nt
	global_load_dwordx4 v[236:239], v[226:227], off offset:256 nt
	s_mov_b64 s[0:1], 0xa0000
	v_lshl_add_u64 v[226:227], v[228:229], 0, s[0:1]
	global_load_dwordx4 v[240:243], v[226:227], off nt
	global_load_dwordx4 v[244:247], v[226:227], off offset:256 nt
	s_mov_b64 s[0:1], 0xb0000
	v_lshl_add_u64 v[226:227], v[228:229], 0, s[0:1]
	global_load_dwordx4 v[248:251], v[226:227], off nt
	global_load_dwordx4 v[252:255], v[226:227], off offset:256 nt
	s_waitcnt vmcnt(0)
	v_lshlrev_b32_e32 v188, 16, v142
	v_and_b32_e32 v189, 0xffff0000, v142
	v_lshlrev_b32_e32 v142, 16, v143
	v_and_b32_e32 v143, 0xffff0000, v143
	v_pk_mul_f32 v[128:129], v[128:129], v[142:143]
	v_lshlrev_b32_e32 v204, 16, v144
	v_and_b32_e32 v205, 0xffff0000, v144
	v_lshlrev_b32_e32 v144, 16, v145
	v_lshlrev_b32_e32 v142, 16, v192
	v_and_b32_e32 v143, 0xffff0000, v192
	v_pk_mul_f32 v[110:111], v[110:111], v[142:143]
	v_lshlrev_b32_e32 v142, 16, v193
	v_and_b32_e32 v143, 0xffff0000, v193
	v_pk_mul_f32 v[112:113], v[112:113], v[142:143]
	v_add_u32_e32 v142, 0x90, v160
	v_and_b32_e32 v145, 0xffff0000, v145
	v_ashrrev_i32_e32 v143, 31, v142
	v_lshlrev_b32_e32 v210, 16, v180
	v_and_b32_e32 v211, 0xffff0000, v180
	v_lshlrev_b32_e32 v180, 16, v181
	v_and_b32_e32 v181, 0xffff0000, v181
	v_pk_mul_f32 v[124:125], v[124:125], v[144:145]
	v_lshlrev_b64 v[144:145], 12, v[142:143]
	v_lshlrev_b32_e32 v206, 16, v176
	v_and_b32_e32 v207, 0xffff0000, v176
	v_lshlrev_b32_e32 v176, 16, v177
	v_and_b32_e32 v177, 0xffff0000, v177
	v_lshlrev_b32_e32 v208, 16, v178
	v_and_b32_e32 v209, 0xffff0000, v178
	v_lshlrev_b32_e32 v178, 16, v179
	v_and_b32_e32 v179, 0xffff0000, v179
	v_pk_mul_f32 v[120:121], v[120:121], v[180:181]
	v_lshl_add_u64 v[144:145], v[170:171], 0, v[144:145]
	v_lshlrev_b32_e32 v180, 16, v194
	v_and_b32_e32 v181, 0xffff0000, v194
	v_pk_mul_f32 v[96:97], v[96:97], v[176:177]
	v_pk_mul_f32 v[92:93], v[92:93], v[178:179]
	v_mov_b64_e32 v[176:177], v[232:233]
	v_mov_b64_e32 v[178:179], v[234:235]
	v_pk_mul_f32 v[106:107], v[106:107], v[180:181]
	v_lshlrev_b32_e32 v180, 16, v195
	v_and_b32_e32 v181, 0xffff0000, v195
	v_lshlrev_b32_e32 v212, 16, v182
	v_and_b32_e32 v213, 0xffff0000, v182
	v_lshlrev_b32_e32 v182, 16, v183
	v_and_b32_e32 v183, 0xffff0000, v183
	v_pk_mul_f32 v[108:109], v[108:109], v[180:181]
	v_lshlrev_b32_e32 v180, 16, v196
	v_and_b32_e32 v181, 0xffff0000, v196
	v_pk_mul_f32 v[116:117], v[116:117], v[182:183]
	v_pk_mul_f32 v[78:79], v[78:79], v[180:181]
	v_mov_b64_e32 v[180:181], v[236:237]
	v_mov_b64_e32 v[182:183], v[238:239]
	v_lshlrev_b32_e32 v144, 16, v198
	v_and_b32_e32 v145, 0xffff0000, v198
	v_pk_mul_f32 v[74:75], v[74:75], v[144:145]
	v_lshlrev_b32_e32 v144, 16, v199
	v_and_b32_e32 v145, 0xffff0000, v199
	v_lshlrev_b32_e32 v214, 16, v184
	v_and_b32_e32 v215, 0xffff0000, v184
	v_lshlrev_b32_e32 v184, 16, v185
	v_and_b32_e32 v185, 0xffff0000, v185
	v_pk_mul_f32 v[76:77], v[76:77], v[144:145]
	v_add_u32_e32 v144, 0xa0, v160
	v_pk_mul_f32 v[88:89], v[88:89], v[184:185]
	v_lshlrev_b32_e32 v184, 16, v197
	v_and_b32_e32 v185, 0xffff0000, v197
	v_ashrrev_i32_e32 v145, 31, v144
	v_pk_mul_f32 v[80:81], v[80:81], v[184:185]
	v_lshlrev_b64 v[184:185], 12, v[144:145]
	v_lshlrev_b32_e32 v216, 16, v186
	v_and_b32_e32 v217, 0xffff0000, v186
	v_lshlrev_b32_e32 v186, 16, v187
	v_and_b32_e32 v187, 0xffff0000, v187
	v_pk_mul_f32 v[126:127], v[126:127], v[188:189]
	v_lshl_add_u64 v[188:189], v[170:171], 0, v[184:185]
	v_pk_mul_f32 v[84:85], v[84:85], v[186:187]
	v_mov_b64_e32 v[184:185], v[240:241]
	v_mov_b64_e32 v[186:187], v[242:243]
	v_lshlrev_b32_e32 v192, 16, v200
	v_and_b32_e32 v193, 0xffff0000, v200
	v_pk_mul_f32 v[102:103], v[102:103], v[192:193]
	v_lshlrev_b32_e32 v192, 16, v201
; __device__ __forceinline__ float bf_lo(unsigned w) { return __uint_as_float(w << 16); }
; __device__ __forceinline__ float bf_hi(unsigned w) { return __uint_as_float(w & 0xffff0000u); }
;     __device__ __forceinline__ bool operator()(f32x4 (&acc)[2][2][4][2], const Unit& u, int wr, int wc, int fr, int fq) const {
;     ...
;                 for (int bj = 0; bj < 2; ++bj) { const u32x4 s = *(const u32x4*)(S + off + bj * HALF);
;                     f32x4 v0 = acc[ai][bj][m][0], v1 = acc[ai][bj][m][1];
;                     v0[0] *= bf_lo(s.x); v0[1] *= bf_hi(s.x); v0[2] *= bf_lo(s.y); v0[3] *= bf_hi(s.y);
;                     v1[0] *= bf_lo(s.z); v1[1] *= bf_hi(s.z); v1[2] *= bf_lo(s.w); v1[3] *= bf_hi(s.w);
;                     acc[ai][bj][m][0] = v0; acc[ai][bj][m][1] = v1; } }
;         if (u.kh == 0) return false;
	v_and_b32_e32 v193, 0xffff0000, v201
	v_pk_mul_f32 v[104:105], v[104:105], v[192:193]
	v_lshlrev_b32_e32 v192, 16, v202
	v_and_b32_e32 v193, 0xffff0000, v202
	v_pk_mul_f32 v[98:99], v[98:99], v[192:193]
	v_mov_b64_e32 v[192:193], v[244:245]
	v_mov_b64_e32 v[194:195], v[246:247]
	v_lshlrev_b32_e32 v188, 16, v138
	v_and_b32_e32 v189, 0xffff0000, v138
	v_lshlrev_b32_e32 v138, 16, v139
	v_and_b32_e32 v139, 0xffff0000, v139
	v_pk_mul_f32 v[72:73], v[72:73], v[138:139]
	v_add_u32_e32 v138, 0xb0, v160
	v_ashrrev_i32_e32 v139, 31, v138
	v_pk_mul_f32 v[70:71], v[70:71], v[188:189]
	v_lshlrev_b64 v[188:189], 12, v[138:139]
	v_lshlrev_b32_e32 v196, 16, v203
	v_and_b32_e32 v197, 0xffff0000, v203
	v_lshl_add_u64 v[170:171], v[170:171], 0, v[188:189]
	v_pk_mul_f32 v[100:101], v[100:101], v[196:197]
	v_mov_b64_e32 v[196:197], v[248:249]
	v_mov_b64_e32 v[198:199], v[250:251]
	v_mov_b64_e32 v[200:201], v[252:253]
	v_mov_b64_e32 v[202:203], v[254:255]
	v_lshlrev_b32_e32 v188, 16, v140
	v_and_b32_e32 v189, 0xffff0000, v140
	v_lshlrev_b32_e32 v140, 16, v141
	v_and_b32_e32 v141, 0xffff0000, v141
	v_pk_mul_f32 v[68:69], v[68:69], v[140:141]
	v_lshlrev_b32_e32 v140, 16, v130
	v_and_b32_e32 v141, 0xffff0000, v130
	v_lshlrev_b32_e32 v130, 16, v131
	v_and_b32_e32 v131, 0xffff0000, v131
	v_pk_mul_f32 v[64:65], v[64:65], v[130:131]
	v_lshlrev_b32_e32 v130, 16, v132
	v_and_b32_e32 v131, 0xffff0000, v132
	v_pk_mul_f32 v[58:59], v[58:59], v[130:131]
	v_lshlrev_b32_e32 v130, 16, v133
	v_and_b32_e32 v131, 0xffff0000, v133
	v_pk_mul_f32 v[60:61], v[60:61], v[130:131]
	v_lshlrev_b32_e32 v130, 16, v134
	v_and_b32_e32 v131, 0xffff0000, v134
	v_pk_mul_f32 v[30:31], v[30:31], v[130:131]
	v_lshlrev_b32_e32 v130, 16, v135
	v_and_b32_e32 v131, 0xffff0000, v135
	v_pk_mul_f32 v[32:33], v[32:33], v[130:131]
	v_lshlrev_b32_e32 v130, 16, v136
	v_and_b32_e32 v131, 0xffff0000, v136
	v_pk_mul_f32 v[26:27], v[26:27], v[130:131]
	v_lshlrev_b32_e32 v130, 16, v137
	v_and_b32_e32 v131, 0xffff0000, v137
	v_pk_mul_f32 v[28:29], v[28:29], v[130:131]
	s_waitcnt vmcnt(0)
	v_lshlrev_b32_e32 v130, 16, v176
	v_and_b32_e32 v131, 0xffff0000, v176
	v_pk_mul_f32 v[54:55], v[54:55], v[130:131]
	v_lshlrev_b32_e32 v130, 16, v177
	v_and_b32_e32 v131, 0xffff0000, v177
	v_pk_mul_f32 v[56:57], v[56:57], v[130:131]
	v_lshlrev_b32_e32 v130, 16, v178
	v_and_b32_e32 v131, 0xffff0000, v178
	v_pk_mul_f32 v[50:51], v[50:51], v[130:131]
	v_lshlrev_b32_e32 v130, 16, v179
	v_and_b32_e32 v131, 0xffff0000, v179
	v_pk_mul_f32 v[52:53], v[52:53], v[130:131]
	v_lshlrev_b32_e32 v130, 16, v180
	v_and_b32_e32 v131, 0xffff0000, v180
	v_pk_mul_f32 v[22:23], v[22:23], v[130:131]
	v_lshlrev_b32_e32 v130, 16, v181
	v_and_b32_e32 v131, 0xffff0000, v181
	v_pk_mul_f32 v[24:25], v[24:25], v[130:131]
	v_lshlrev_b32_e32 v130, 16, v182
	v_and_b32_e32 v131, 0xffff0000, v182
	v_pk_mul_f32 v[18:19], v[18:19], v[130:131]
	v_lshlrev_b32_e32 v130, 16, v183
	v_and_b32_e32 v131, 0xffff0000, v183
	v_pk_mul_f32 v[20:21], v[20:21], v[130:131]
	v_pk_mul_f32 v[122:123], v[122:123], v[204:205]
	v_pk_mul_f32 v[94:95], v[94:95], v[206:207]
	v_lshlrev_b32_e32 v130, 16, v184
	v_and_b32_e32 v131, 0xffff0000, v184
	v_pk_mul_f32 v[46:47], v[46:47], v[130:131]
	v_lshlrev_b32_e32 v130, 16, v185
	v_and_b32_e32 v131, 0xffff0000, v185
	v_pk_mul_f32 v[48:49], v[48:49], v[130:131]
	v_lshlrev_b32_e32 v130, 16, v186
	v_and_b32_e32 v131, 0xffff0000, v186
	v_pk_mul_f32 v[42:43], v[42:43], v[130:131]
	v_lshlrev_b32_e32 v130, 16, v187
	v_and_b32_e32 v131, 0xffff0000, v187
	v_pk_mul_f32 v[44:45], v[44:45], v[130:131]
	v_lshlrev_b32_e32 v130, 16, v192
	v_and_b32_e32 v131, 0xffff0000, v192
	v_pk_mul_f32 v[14:15], v[14:15], v[130:131]
	v_lshlrev_b32_e32 v130, 16, v193
	v_and_b32_e32 v131, 0xffff0000, v193
	v_pk_mul_f32 v[16:17], v[16:17], v[130:131]
	v_lshlrev_b32_e32 v130, 16, v194
	v_and_b32_e32 v131, 0xffff0000, v194
	v_pk_mul_f32 v[10:11], v[10:11], v[130:131]
	v_lshlrev_b32_e32 v130, 16, v195
	v_and_b32_e32 v131, 0xffff0000, v195
	v_pk_mul_f32 v[12:13], v[12:13], v[130:131]
	v_lshlrev_b32_e32 v130, 16, v196
	v_and_b32_e32 v131, 0xffff0000, v196
	v_pk_mul_f32 v[38:39], v[38:39], v[130:131]
	v_lshlrev_b32_e32 v130, 16, v197
	v_and_b32_e32 v131, 0xffff0000, v197
	v_pk_mul_f32 v[40:41], v[40:41], v[130:131]
	v_lshlrev_b32_e32 v130, 16, v198
	v_and_b32_e32 v131, 0xffff0000, v198
	v_pk_mul_f32 v[34:35], v[34:35], v[130:131]
	v_lshlrev_b32_e32 v130, 16, v199
	v_and_b32_e32 v131, 0xffff0000, v199
	v_pk_mul_f32 v[36:37], v[36:37], v[130:131]
	v_lshlrev_b32_e32 v130, 16, v200
	v_and_b32_e32 v131, 0xffff0000, v200
	v_pk_mul_f32 v[6:7], v[6:7], v[130:131]
	v_lshlrev_b32_e32 v130, 16, v201
	v_and_b32_e32 v131, 0xffff0000, v201
	v_pk_mul_f32 v[8:9], v[8:9], v[130:131]
	v_lshlrev_b32_e32 v130, 16, v202
	v_and_b32_e32 v131, 0xffff0000, v202
	v_pk_mul_f32 v[2:3], v[2:3], v[130:131]
	v_lshlrev_b32_e32 v130, 16, v203
	v_and_b32_e32 v131, 0xffff0000, v203
	v_pk_mul_f32 v[90:91], v[90:91], v[208:209]
	v_pk_mul_f32 v[118:119], v[118:119], v[210:211]
	v_pk_mul_f32 v[114:115], v[114:115], v[212:213]
	v_pk_mul_f32 v[86:87], v[86:87], v[214:215]
	v_pk_mul_f32 v[82:83], v[82:83], v[216:217]
	v_pk_mul_f32 v[66:67], v[66:67], v[188:189]
	v_pk_mul_f32 v[62:63], v[62:63], v[140:141]
	v_pk_mul_f32 v[4:5], v[4:5], v[130:131]
	s_cbranch_vccnz .LBB0_818
; __device__ __forceinline__ unsigned pk_bf16(float lo, float hi) { const f32x2_t v = {lo, hi}; return __builtin_bit_cast(unsigned, __builtin_convertvector(v, bf16x2_t)); }
;     __device__ __forceinline__ bool operator()(f32x4 (&acc)[2][2][4][2], const Unit& u, int wr, int wc, int fr, int fq) const {
;     ...
; #pragma unroll
;         for (int ai = 0; ai < 2; ++ai)
; #pragma unroll
;             for (int m = 0; m < 4; ++m) { const size_t off = (size_t)(r0 + ai * HALF + m * 16) * LDP + c0;
; #pragma unroll
;                 for (int bj = 0; bj < 2; ++bj) { const f32x4 v0 = acc[ai][bj][m][0], v1 = acc[ai][bj][m][1];
;                     u32x4 w; w.x = pk_bf16(v0[0], v0[1]); w.y = pk_bf16(v0[2], v0[3]); w.z = pk_bf16(v1[0], v1[1]); w.w = pk_bf16(v1[2], v1[3]);
;                     *(u32x4*)(MG + off + bj * HALF) = w; } }
	v_mov_b64_e32 v[134:135], s[12:13]
	v_mad_i64_i32 v[136:137], s[0:1], v160, s60, v[134:135]
	v_lshlrev_b64 v[140:141], 1, v[158:159]
	v_cvt_pk_bf16_f32 v130, v126, v127
	v_cvt_pk_bf16_f32 v131, v128, v129
	v_cvt_pk_bf16_f32 v132, v122, v123
	v_cvt_pk_bf16_f32 v133, v124, v125
	v_lshl_add_u64 v[136:137], v[136:137], 0, v[140:141]
	global_store_dwordx4 v[136:137], v[130:133], off
	s_nop 1
	v_cvt_pk_bf16_f32 v130, v94, v95
	v_cvt_pk_bf16_f32 v131, v96, v97
	v_cvt_pk_bf16_f32 v132, v90, v91
	v_cvt_pk_bf16_f32 v133, v92, v93
	global_store_dwordx4 v[136:137], v[130:133], off offset:256
	v_mad_i64_i32 v[136:137], s[0:1], v162, s60, v[134:135]
	s_nop 0
	v_cvt_pk_bf16_f32 v130, v118, v119
	v_cvt_pk_bf16_f32 v131, v120, v121
	v_cvt_pk_bf16_f32 v132, v114, v115
	v_cvt_pk_bf16_f32 v133, v116, v117
	v_lshl_add_u64 v[136:137], v[136:137], 0, v[140:141]
	global_store_dwordx4 v[136:137], v[130:133], off
	s_nop 1
	v_cvt_pk_bf16_f32 v130, v86, v87
	v_cvt_pk_bf16_f32 v131, v88, v89
	v_cvt_pk_bf16_f32 v132, v82, v83
	v_cvt_pk_bf16_f32 v133, v84, v85
	global_store_dwordx4 v[136:137], v[130:133], off offset:256
	v_mad_i64_i32 v[136:137], s[0:1], v164, s60, v[134:135]
	s_nop 0
	v_cvt_pk_bf16_f32 v130, v110, v111
	v_cvt_pk_bf16_f32 v131, v112, v113
	v_cvt_pk_bf16_f32 v132, v106, v107
	v_cvt_pk_bf16_f32 v133, v108, v109
	v_lshl_add_u64 v[136:137], v[136:137], 0, v[140:141]
	global_store_dwordx4 v[136:137], v[130:133], off
	s_nop 1
	v_cvt_pk_bf16_f32 v130, v78, v79
	v_cvt_pk_bf16_f32 v131, v80, v81
	v_cvt_pk_bf16_f32 v132, v74, v75
	v_cvt_pk_bf16_f32 v133, v76, v77
	global_store_dwordx4 v[136:137], v[130:133], off offset:256
	v_mad_i64_i32 v[136:137], s[0:1], v166, s60, v[134:135]
	s_nop 0
	v_cvt_pk_bf16_f32 v130, v102, v103
	v_cvt_pk_bf16_f32 v131, v104, v105
	v_cvt_pk_bf16_f32 v132, v98, v99
	v_cvt_pk_bf16_f32 v133, v100, v101
	v_lshl_add_u64 v[136:137], v[136:137], 0, v[140:141]
	global_store_dwordx4 v[136:137], v[130:133], off
	s_nop 1
	v_cvt_pk_bf16_f32 v130, v70, v71
	v_cvt_pk_bf16_f32 v131, v72, v73
	v_cvt_pk_bf16_f32 v132, v66, v67
	v_cvt_pk_bf16_f32 v133, v68, v69
	global_store_dwordx4 v[136:137], v[130:133], off offset:256
	v_mad_i64_i32 v[136:137], s[0:1], v168, s60, v[134:135]
	s_nop 0
	v_cvt_pk_bf16_f32 v130, v62, v63
	v_cvt_pk_bf16_f32 v131, v64, v65
	v_cvt_pk_bf16_f32 v132, v58, v59
	v_cvt_pk_bf16_f32 v133, v60, v61
	v_lshl_add_u64 v[136:137], v[136:137], 0, v[140:141]
	global_store_dwordx4 v[136:137], v[130:133], off
	s_nop 1
	v_cvt_pk_bf16_f32 v130, v30, v31
	v_cvt_pk_bf16_f32 v131, v32, v33
	v_cvt_pk_bf16_f32 v132, v26, v27
	v_cvt_pk_bf16_f32 v133, v28, v29
	global_store_dwordx4 v[136:137], v[130:133], off offset:256
	v_mad_i64_i32 v[136:137], s[0:1], v142, s60, v[134:135]
	s_nop 0
	v_cvt_pk_bf16_f32 v130, v54, v55
	v_cvt_pk_bf16_f32 v131, v56, v57
	v_cvt_pk_bf16_f32 v132, v50, v51
	v_cvt_pk_bf16_f32 v133, v52, v53
	v_lshl_add_u64 v[136:137], v[136:137], 0, v[140:141]
	global_store_dwordx4 v[136:137], v[130:133], off
	s_nop 1
	v_cvt_pk_bf16_f32 v130, v22, v23
	v_cvt_pk_bf16_f32 v131, v24, v25
	v_cvt_pk_bf16_f32 v132, v18, v19
	v_cvt_pk_bf16_f32 v133, v20, v21
	global_store_dwordx4 v[136:137], v[130:133], off offset:256
	v_mad_i64_i32 v[136:137], s[0:1], v144, s60, v[134:135]
	s_nop 0
	v_cvt_pk_bf16_f32 v130, v46, v47
	v_cvt_pk_bf16_f32 v131, v48, v49
	v_cvt_pk_bf16_f32 v132, v42, v43
	v_cvt_pk_bf16_f32 v133, v44, v45
	v_lshl_add_u64 v[136:137], v[136:137], 0, v[140:141]
	global_store_dwordx4 v[136:137], v[130:133], off
	v_mad_i64_i32 v[134:135], s[0:1], v138, s60, v[134:135]
	s_nop 0
	v_cvt_pk_bf16_f32 v130, v14, v15
	v_cvt_pk_bf16_f32 v131, v16, v17
	v_cvt_pk_bf16_f32 v132, v10, v11
	v_cvt_pk_bf16_f32 v133, v12, v13
	global_store_dwordx4 v[136:137], v[130:133], off offset:256
	v_lshl_add_u64 v[134:135], v[134:135], 0, v[140:141]
	s_nop 0
	v_cvt_pk_bf16_f32 v130, v38, v39
	v_cvt_pk_bf16_f32 v131, v40, v41
	v_cvt_pk_bf16_f32 v132, v34, v35
	v_cvt_pk_bf16_f32 v133, v36, v37
	global_store_dwordx4 v[134:135], v[130:133], off
	s_nop 1
	v_cvt_pk_bf16_f32 v130, v6, v7
	v_cvt_pk_bf16_f32 v131, v8, v9
	v_cvt_pk_bf16_f32 v132, v2, v3
	v_cvt_pk_bf16_f32 v133, v4, v5
	global_store_dwordx4 v[134:135], v[130:133], off offset:256

; #define G_STAGE(bufoff, gbase, voff) do { _Pragma("unroll") for (int _i = 0; _i < 2; ++_i) \
;         __builtin_amdgcn_global_load_lds((const unsigned*)((const char*)(gbase) + (voff)[_i]), (LAS unsigned*)(lds + (bufoff) + ldsw + _i * 8192), 16, 0, 0); } while (0)
; #define G_WAIT_V(n) asm volatile("s_waitcnt vmcnt(" #n ")" ::: "memory")
; #define G_WAIT_L(n) asm volatile("s_waitcnt lgkmcnt(" #n ")" ::: "memory")
; #define G_BAR __builtin_amdgcn_s_barrier()
; #define G_SCHED __builtin_amdgcn_sched_barrier(0)
; template <int MODE  , class Epi, class Sched>
; __device__ __forceinline__ void gemm_phase(LAS unsigned char* lds, const GemmDesc g, const Sched& S, const Epi& E) {
;     ...
;             G_LDB(B0, 0, 0); G_SCHED; G_LDA(At, 0, 0); G_STAGE(G_SA(1, 1), a1 + hstepA, voffA);
;             G_WAIT_L(8); G_BAR; G_WAIT_L(0); G_MMA(0, 0, At, B0); G_BAR; G_SCHED;
;             G_LDB(B1, 0, 1); G_STAGE(G_SB(0, 0), b2, voffB);
;             G_BAR; G_WAIT_L(0); G_MMA(0, 1, At, B1); G_BAR;
;             G_LDA(At, 0, 1); G_STAGE(G_SA(0, 0), a2, voffA);
;             G_BAR; G_WAIT_L(0); G_MMA(1, 0, At, B0); G_BAR; G_SCHED;
;             G_STAGE(G_SB(0, 1), b2 + hstepB, voffB);
;             G_WAIT_V(6); G_BAR; G_MMA(1, 1, At, B1); G_BAR;
.LBB0_897:
	s_add_u32 s42, s40, 0x100
	s_addc_u32 s43, s41, 0
	s_cmp_eq_u32 s71, 12
	s_cselect_b32 s47, s21, s43
	s_cselect_b32 s46, s20, s42
	s_cselect_b32 s45, s3, s70
	s_cselect_b32 s44, s2, s19
	s_add_u32 s98, s40, 0x84080
	s_addc_u32 s99, s41, 0
	s_add_i32 m0, s50, 0xc000
	ds_read_b128 v[158:161], v176
	ds_read_b128 v[162:165], v176 offset:1024
	ds_read_b128 v[166:169], v176 offset:2048
	ds_read_b128 v[170:173], v176 offset:3072
	ds_read_b128 v[178:181], v176 offset:4096
	ds_read_b128 v[182:185], v176 offset:5120
	ds_read_b128 v[186:189], v176 offset:6144
	ds_read_b128 v[192:195], v176 offset:7168
	global_load_lds_dwordx4 v146, s[98:99]
	s_add_i32 m0, s50, 0xe000
	s_nop 0
	global_load_lds_dwordx4 v150, s[98:99]
	s_waitcnt lgkmcnt(8)
	s_barrier
	s_waitcnt lgkmcnt(0)
	v_mfma_f32_16x16x32_bf16 v[126:129], v[232:235], v[158:161], v[126:129]
	v_mfma_f32_16x16x32_bf16 v[122:125], v[240:243], v[158:161], v[122:125]
	v_mfma_f32_16x16x32_bf16 v[118:121], v[232:235], v[166:169], v[118:121]
	v_mfma_f32_16x16x32_bf16 v[114:117], v[240:243], v[166:169], v[114:117]
	v_mfma_f32_16x16x32_bf16 v[110:113], v[232:235], v[178:181], v[110:113]
	v_mfma_f32_16x16x32_bf16 v[106:109], v[240:243], v[178:181], v[106:109]
	v_mfma_f32_16x16x32_bf16 v[102:105], v[232:235], v[186:189], v[102:105]
	v_mfma_f32_16x16x32_bf16 v[98:101], v[240:243], v[186:189], v[98:101]
	v_mfma_f32_16x16x32_bf16 v[126:129], v[236:239], v[162:165], v[126:129]
	v_mfma_f32_16x16x32_bf16 v[122:125], v[244:247], v[162:165], v[122:125]
	v_mfma_f32_16x16x32_bf16 v[118:121], v[236:239], v[170:173], v[118:121]
	v_mfma_f32_16x16x32_bf16 v[114:117], v[244:247], v[170:173], v[114:117]
	v_mfma_f32_16x16x32_bf16 v[110:113], v[236:239], v[182:185], v[110:113]
	v_mfma_f32_16x16x32_bf16 v[106:109], v[244:247], v[182:185], v[106:109]
	v_mfma_f32_16x16x32_bf16 v[102:105], v[236:239], v[192:195], v[102:105]
	v_mfma_f32_16x16x32_bf16 v[98:101], v[244:247], v[192:195], v[98:101]
	s_barrier
	s_add_i32 s0, s57, s49
	v_add_u32_e32 v177, s58, v174
	s_mov_b32 m0, s0
	ds_read_b128 v[196:199], v177
	ds_read_b128 v[200:203], v177 offset:1024
	ds_read_b128 v[204:207], v177 offset:2048
	ds_read_b128 v[208:211], v177 offset:3072
	global_load_lds_dwordx4 v148, s[44:45]
	s_add_i32 m0, s0, 0x2000
	s_nop 0
	global_load_lds_dwordx4 v152, s[44:45]
	s_barrier
	s_waitcnt lgkmcnt(0)
	v_mfma_f32_16x16x32_bf16 v[94:97], v[196:199], v[158:161], v[94:97]
	v_mfma_f32_16x16x32_bf16 v[90:93], v[204:207], v[158:161], v[90:93]
	v_mfma_f32_16x16x32_bf16 v[86:89], v[196:199], v[166:169], v[86:89]
	v_mfma_f32_16x16x32_bf16 v[82:85], v[204:207], v[166:169], v[82:85]
	v_mfma_f32_16x16x32_bf16 v[78:81], v[196:199], v[178:181], v[78:81]
	v_mfma_f32_16x16x32_bf16 v[74:77], v[204:207], v[178:181], v[74:77]
	v_mfma_f32_16x16x32_bf16 v[70:73], v[196:199], v[186:189], v[70:73]
	v_mfma_f32_16x16x32_bf16 v[66:69], v[204:207], v[186:189], v[66:69]
	v_mfma_f32_16x16x32_bf16 v[94:97], v[200:203], v[162:165], v[94:97]
	v_mfma_f32_16x16x32_bf16 v[90:93], v[208:211], v[162:165], v[90:93]
	v_mfma_f32_16x16x32_bf16 v[86:89], v[200:203], v[170:173], v[86:89]
	v_mfma_f32_16x16x32_bf16 v[82:85], v[208:211], v[170:173], v[82:85]
	v_mfma_f32_16x16x32_bf16 v[78:81], v[200:203], v[182:185], v[78:81]
	v_mfma_f32_16x16x32_bf16 v[74:77], v[208:211], v[182:185], v[74:77]
	v_mfma_f32_16x16x32_bf16 v[70:73], v[200:203], v[192:195], v[70:73]
	v_mfma_f32_16x16x32_bf16 v[66:69], v[208:211], v[192:195], v[66:69]
	s_mov_b32 m0, s50
	s_barrier
	ds_read_b128 v[158:161], v176 offset:16384
	ds_read_b128 v[162:165], v176 offset:17408
	ds_read_b128 v[166:169], v176 offset:18432
	ds_read_b128 v[170:173], v176 offset:19456
	ds_read_b128 v[178:181], v176 offset:20480
	ds_read_b128 v[182:185], v176 offset:21504
	ds_read_b128 v[186:189], v176 offset:22528
	ds_read_b128 v[192:195], v176 offset:23552
	global_load_lds_dwordx4 v146, s[46:47]
	s_mov_b32 m0, s51
	s_nop 0
	global_load_lds_dwordx4 v150, s[46:47]
	s_waitcnt vmcnt(10)
	s_barrier
	s_waitcnt lgkmcnt(0)
	v_mfma_f32_16x16x32_bf16 v[62:65], v[232:235], v[158:161], v[62:65]
	v_mfma_f32_16x16x32_bf16 v[58:61], v[240:243], v[158:161], v[58:61]
	v_mfma_f32_16x16x32_bf16 v[54:57], v[232:235], v[166:169], v[54:57]
	v_mfma_f32_16x16x32_bf16 v[50:53], v[240:243], v[166:169], v[50:53]
	v_mfma_f32_16x16x32_bf16 v[46:49], v[232:235], v[178:181], v[46:49]
	v_mfma_f32_16x16x32_bf16 v[42:45], v[240:243], v[178:181], v[42:45]
	v_mfma_f32_16x16x32_bf16 v[38:41], v[232:235], v[186:189], v[38:41]
	v_mfma_f32_16x16x32_bf16 v[34:37], v[240:243], v[186:189], v[34:37]
	v_mfma_f32_16x16x32_bf16 v[62:65], v[236:239], v[162:165], v[62:65]
	v_mfma_f32_16x16x32_bf16 v[58:61], v[244:247], v[162:165], v[58:61]
	v_mfma_f32_16x16x32_bf16 v[54:57], v[236:239], v[170:173], v[54:57]
	v_mfma_f32_16x16x32_bf16 v[50:53], v[244:247], v[170:173], v[50:53]
	v_mfma_f32_16x16x32_bf16 v[46:49], v[236:239], v[182:185], v[46:49]
	v_mfma_f32_16x16x32_bf16 v[42:45], v[244:247], v[182:185], v[42:45]
	v_mfma_f32_16x16x32_bf16 v[38:41], v[236:239], v[192:195], v[38:41]
	v_mfma_f32_16x16x32_bf16 v[34:37], v[244:247], v[192:195], v[34:37]
	s_barrier
	v_add_u32_e32 v142, 0x18000, v174
	ds_read_b128 v[130:133], v142
	ds_read_b128 v[134:137], v142 offset:1024
	ds_read_b128 v[138:141], v142 offset:2048
	ds_read_b128 v[142:145], v142 offset:3072
	s_add_u32 s0, s44, 0x84000
	s_addc_u32 s1, s45, 0
	s_add_i32 s10, s58, s49
	s_mov_b32 m0, s10
	s_nop 0
	global_load_lds_dwordx4 v148, s[0:1]
	s_add_i32 m0, s10, 0x2000
	s_nop 0
	global_load_lds_dwordx4 v152, s[0:1]
	s_waitcnt vmcnt(6)
	s_barrier
; #define G_STAGE(bufoff, gbase, voff) do { _Pragma("unroll") for (int _i = 0; _i < 2; ++_i) \
;         __builtin_amdgcn_global_load_lds((const unsigned*)((const char*)(gbase) + (voff)[_i]), (LAS unsigned*)(lds + (bufoff) + ldsw + _i * 8192), 16, 0, 0); } while (0)
; #define G_WAIT_V(n) asm volatile("s_waitcnt vmcnt(" #n ")" ::: "memory")
; #define G_WAIT_L(n) asm volatile("s_waitcnt lgkmcnt(" #n ")" ::: "memory")
; #define G_BAR __builtin_amdgcn_s_barrier()
; #define G_SCHED __builtin_amdgcn_sched_barrier(0)
; template <int MODE  , class Epi, class Sched>
; __device__ __forceinline__ void gemm_phase(LAS unsigned char* lds, const GemmDesc g, const Sched& S, const Epi& E) {
;     ...
;             G_WAIT_V(6); G_BAR; G_MMA(1, 1, At, B1); G_BAR;
;             G_LDB(B0, 1, 0); G_SCHED; G_LDA(At, 1, 0); G_STAGE(G_SA(0, 1), a2 + hstepA, voffA);
;             G_WAIT_L(8); G_BAR; G_WAIT_L(0); G_MMA(0, 0, At, B0); G_BAR; G_SCHED;
;             G_LDB(B1, 1, 1); G_STAGE(G_SB(1, 0), b3, voffB);
;             G_BAR; G_WAIT_L(0); G_MMA(0, 1, At, B1); G_BAR;
;             G_LDA(At, 1, 1); G_STAGE(G_SA(1, 0), a3, voffA);
;             G_BAR; G_WAIT_L(0); G_MMA(1, 0, At, B0); G_BAR; G_SCHED;
	v_mfma_f32_16x16x32_bf16 v[30:33], v[196:199], v[158:161], v[30:33]
	v_mfma_f32_16x16x32_bf16 v[26:29], v[204:207], v[158:161], v[26:29]
	v_mfma_f32_16x16x32_bf16 v[22:25], v[196:199], v[166:169], v[22:25]
	v_mfma_f32_16x16x32_bf16 v[18:21], v[204:207], v[166:169], v[18:21]
	v_mfma_f32_16x16x32_bf16 v[14:17], v[196:199], v[178:181], v[14:17]
	v_mfma_f32_16x16x32_bf16 v[10:13], v[204:207], v[178:181], v[10:13]
	v_mfma_f32_16x16x32_bf16 v[6:9], v[196:199], v[186:189], v[6:9]
	v_mfma_f32_16x16x32_bf16 v[2:5], v[204:207], v[186:189], v[2:5]
	v_mfma_f32_16x16x32_bf16 v[30:33], v[200:203], v[162:165], v[30:33]
	v_mfma_f32_16x16x32_bf16 v[26:29], v[208:211], v[162:165], v[26:29]
	v_mfma_f32_16x16x32_bf16 v[22:25], v[200:203], v[170:173], v[22:25]
	v_mfma_f32_16x16x32_bf16 v[18:21], v[208:211], v[170:173], v[18:21]
	v_mfma_f32_16x16x32_bf16 v[14:17], v[200:203], v[182:185], v[14:17]
	v_mfma_f32_16x16x32_bf16 v[10:13], v[208:211], v[182:185], v[10:13]
	v_mfma_f32_16x16x32_bf16 v[6:9], v[200:203], v[192:195], v[6:9]
	v_mfma_f32_16x16x32_bf16 v[2:5], v[208:211], v[192:195], v[2:5]
	s_add_i32 s10, 0, 0x18000
	s_barrier
	s_add_u32 s0, s46, 0x84000
	s_addc_u32 s1, s47, 0
	s_mov_b32 m0, s52
	ds_read_b128 v[158:161], v176 offset:32768
	ds_read_b128 v[162:165], v176 offset:33792
	ds_read_b128 v[166:169], v176 offset:34816
	ds_read_b128 v[170:173], v176 offset:35840
	ds_read_b128 v[178:181], v176 offset:36864
	ds_read_b128 v[182:185], v176 offset:37888
	ds_read_b128 v[186:189], v176 offset:38912
	ds_read_b128 v[192:195], v176 offset:39936
	global_load_lds_dwordx4 v146, s[0:1]
	s_mov_b32 m0, s53
	s_nop 0
	global_load_lds_dwordx4 v150, s[0:1]
	s_waitcnt lgkmcnt(8)
	s_barrier
	s_waitcnt lgkmcnt(0)
	v_mfma_f32_16x16x32_bf16 v[126:129], v[130:133], v[158:161], v[126:129]
	v_mfma_f32_16x16x32_bf16 v[122:125], v[138:141], v[158:161], v[122:125]
	v_mfma_f32_16x16x32_bf16 v[118:121], v[130:133], v[166:169], v[118:121]
	v_mfma_f32_16x16x32_bf16 v[114:117], v[138:141], v[166:169], v[114:117]
	v_mfma_f32_16x16x32_bf16 v[110:113], v[130:133], v[178:181], v[110:113]
	v_mfma_f32_16x16x32_bf16 v[106:109], v[138:141], v[178:181], v[106:109]
	v_mfma_f32_16x16x32_bf16 v[102:105], v[130:133], v[186:189], v[102:105]
	v_mfma_f32_16x16x32_bf16 v[98:101], v[138:141], v[186:189], v[98:101]
	v_mfma_f32_16x16x32_bf16 v[126:129], v[134:137], v[162:165], v[126:129]
	v_mfma_f32_16x16x32_bf16 v[122:125], v[142:145], v[162:165], v[122:125]
	v_mfma_f32_16x16x32_bf16 v[118:121], v[134:137], v[170:173], v[118:121]
	v_mfma_f32_16x16x32_bf16 v[114:117], v[142:145], v[170:173], v[114:117]
	v_mfma_f32_16x16x32_bf16 v[110:113], v[134:137], v[182:185], v[110:113]
	v_mfma_f32_16x16x32_bf16 v[106:109], v[142:145], v[182:185], v[106:109]
	v_mfma_f32_16x16x32_bf16 v[102:105], v[134:137], v[192:195], v[102:105]
	v_mfma_f32_16x16x32_bf16 v[98:101], v[142:145], v[192:195], v[98:101]
	s_barrier
	s_add_i32 s11, 0, 0x1c000
	s_add_i32 s0, s10, s49
	v_add_u32_e32 v177, s11, v174
	s_add_u32 s98, s44, 0x80
	s_addc_u32 s99, s45, 0
	s_mov_b32 m0, s0
	ds_read_b128 v[196:199], v177
	ds_read_b128 v[200:203], v177 offset:1024
	ds_read_b128 v[204:207], v177 offset:2048
	ds_read_b128 v[208:211], v177 offset:3072
	global_load_lds_dwordx4 v148, s[98:99]
	s_add_i32 m0, s0, 0x2000
	s_nop 0
	global_load_lds_dwordx4 v152, s[98:99]
	s_barrier
	s_waitcnt lgkmcnt(0)
	v_mfma_f32_16x16x32_bf16 v[94:97], v[196:199], v[158:161], v[94:97]
	v_mfma_f32_16x16x32_bf16 v[90:93], v[204:207], v[158:161], v[90:93]
	v_mfma_f32_16x16x32_bf16 v[86:89], v[196:199], v[166:169], v[86:89]
	v_mfma_f32_16x16x32_bf16 v[82:85], v[204:207], v[166:169], v[82:85]
	v_mfma_f32_16x16x32_bf16 v[78:81], v[196:199], v[178:181], v[78:81]
	v_mfma_f32_16x16x32_bf16 v[74:77], v[204:207], v[178:181], v[74:77]
	v_mfma_f32_16x16x32_bf16 v[70:73], v[196:199], v[186:189], v[70:73]
	v_mfma_f32_16x16x32_bf16 v[66:69], v[204:207], v[186:189], v[66:69]
	v_mfma_f32_16x16x32_bf16 v[94:97], v[200:203], v[162:165], v[94:97]
	v_mfma_f32_16x16x32_bf16 v[90:93], v[208:211], v[162:165], v[90:93]
	v_mfma_f32_16x16x32_bf16 v[86:89], v[200:203], v[170:173], v[86:89]
	v_mfma_f32_16x16x32_bf16 v[82:85], v[208:211], v[170:173], v[82:85]
	v_mfma_f32_16x16x32_bf16 v[78:81], v[200:203], v[182:185], v[78:81]
	v_mfma_f32_16x16x32_bf16 v[74:77], v[208:211], v[182:185], v[74:77]
	v_mfma_f32_16x16x32_bf16 v[70:73], v[200:203], v[192:195], v[70:73]
	v_mfma_f32_16x16x32_bf16 v[66:69], v[208:211], v[192:195], v[66:69]
	s_mov_b32 m0, s54
	s_add_u32 s98, s46, 0x80
	s_addc_u32 s99, s47, 0
	s_barrier
; #define G_STAGE(bufoff, gbase, voff) do { _Pragma("unroll") for (int _i = 0; _i < 2; ++_i) \
;         __builtin_amdgcn_global_load_lds((const unsigned*)((const char*)(gbase) + (voff)[_i]), (LAS unsigned*)(lds + (bufoff) + ldsw + _i * 8192), 16, 0, 0); } while (0)
; #define G_WAIT_V(n) asm volatile("s_waitcnt vmcnt(" #n ")" ::: "memory")
; #define G_WAIT_L(n) asm volatile("s_waitcnt lgkmcnt(" #n ")" ::: "memory")
; #define G_BAR __builtin_amdgcn_s_barrier()
; #define G_SCHED __builtin_amdgcn_sched_barrier(0)
; template <int MODE  , class Epi, class Sched>
; __device__ __forceinline__ void gemm_phase(LAS unsigned char* lds, const GemmDesc g, const Sched& S, const Epi& E) {
;     ...
;             G_LDA(At, 1, 1); G_STAGE(G_SA(1, 0), a3, voffA);
;             G_BAR; G_WAIT_L(0); G_MMA(1, 0, At, B0); G_BAR; G_SCHED;
;             G_STAGE(G_SB(1, 1), b3 + hstepB, voffB);
;             G_WAIT_V(6); G_BAR; G_MMA(1, 1, At, B1); G_BAR;
;         }
	ds_read_b128 v[158:161], v176 offset:49152
	ds_read_b128 v[162:165], v176 offset:50176
	ds_read_b128 v[166:169], v176 offset:51200
	ds_read_b128 v[170:173], v176 offset:52224
	ds_read_b128 v[178:181], v176 offset:53248
	ds_read_b128 v[182:185], v176 offset:54272
	ds_read_b128 v[186:189], v176 offset:55296
	ds_read_b128 v[192:195], v176 offset:56320
	global_load_lds_dwordx4 v146, s[98:99]
	s_mov_b32 m0, s55
	s_nop 0
	global_load_lds_dwordx4 v150, s[98:99]
	s_waitcnt vmcnt(10)
	s_barrier
	s_waitcnt lgkmcnt(0)
	v_mfma_f32_16x16x32_bf16 v[62:65], v[130:133], v[158:161], v[62:65]
	v_mfma_f32_16x16x32_bf16 v[58:61], v[138:141], v[158:161], v[58:61]
	v_mfma_f32_16x16x32_bf16 v[54:57], v[130:133], v[166:169], v[54:57]
	v_mfma_f32_16x16x32_bf16 v[50:53], v[138:141], v[166:169], v[50:53]
	v_mfma_f32_16x16x32_bf16 v[46:49], v[130:133], v[178:181], v[46:49]
	v_mfma_f32_16x16x32_bf16 v[42:45], v[138:141], v[178:181], v[42:45]
	v_mfma_f32_16x16x32_bf16 v[38:41], v[130:133], v[186:189], v[38:41]
	v_mfma_f32_16x16x32_bf16 v[34:37], v[138:141], v[186:189], v[34:37]
	v_mfma_f32_16x16x32_bf16 v[62:65], v[134:137], v[162:165], v[62:65]
	v_mfma_f32_16x16x32_bf16 v[58:61], v[142:145], v[162:165], v[58:61]
	v_mfma_f32_16x16x32_bf16 v[54:57], v[134:137], v[170:173], v[54:57]
	v_mfma_f32_16x16x32_bf16 v[50:53], v[142:145], v[170:173], v[50:53]
	v_mfma_f32_16x16x32_bf16 v[46:49], v[134:137], v[182:185], v[46:49]
	v_mfma_f32_16x16x32_bf16 v[42:45], v[142:145], v[182:185], v[42:45]
	v_mfma_f32_16x16x32_bf16 v[38:41], v[134:137], v[192:195], v[38:41]
	v_mfma_f32_16x16x32_bf16 v[34:37], v[142:145], v[192:195], v[34:37]
	s_barrier
	v_add_u32_e32 v244, s57, v174
	ds_read_b128 v[232:235], v244
	ds_read_b128 v[236:239], v244 offset:1024
	ds_read_b128 v[240:243], v244 offset:2048
	ds_read_b128 v[244:247], v244 offset:3072
	s_add_u32 s0, s44, 0x84080
	s_addc_u32 s1, s45, 0
	s_add_i32 s10, s11, s49
	s_mov_b32 m0, s10
	s_nop 0
	global_load_lds_dwordx4 v148, s[0:1]
	s_add_i32 m0, s10, 0x2000
	s_nop 0
	global_load_lds_dwordx4 v152, s[0:1]
	s_waitcnt vmcnt(6)
	s_barrier
	v_mfma_f32_16x16x32_bf16 v[30:33], v[196:199], v[158:161], v[30:33]
	s_add_i32 s71, s71, 2
	s_add_u32 s19, s19, 0x100
	s_addc_u32 s70, s70, 0
	s_cmp_gt_u32 s71, 13
	s_mov_b64 s[40:41], s[42:43]
	v_mfma_f32_16x16x32_bf16 v[26:29], v[204:207], v[158:161], v[26:29]
	v_mfma_f32_16x16x32_bf16 v[22:25], v[196:199], v[166:169], v[22:25]
	v_mfma_f32_16x16x32_bf16 v[18:21], v[204:207], v[166:169], v[18:21]
	v_mfma_f32_16x16x32_bf16 v[14:17], v[196:199], v[178:181], v[14:17]
	v_mfma_f32_16x16x32_bf16 v[10:13], v[204:207], v[178:181], v[10:13]
	v_mfma_f32_16x16x32_bf16 v[6:9], v[196:199], v[186:189], v[6:9]
	v_mfma_f32_16x16x32_bf16 v[2:5], v[204:207], v[186:189], v[2:5]
	v_mfma_f32_16x16x32_bf16 v[30:33], v[200:203], v[162:165], v[30:33]
	v_mfma_f32_16x16x32_bf16 v[26:29], v[208:211], v[162:165], v[26:29]
	v_mfma_f32_16x16x32_bf16 v[22:25], v[200:203], v[170:173], v[22:25]
	v_mfma_f32_16x16x32_bf16 v[18:21], v[208:211], v[170:173], v[18:21]
	v_mfma_f32_16x16x32_bf16 v[14:17], v[200:203], v[182:185], v[14:17]
	v_mfma_f32_16x16x32_bf16 v[10:13], v[208:211], v[182:185], v[10:13]
	v_mfma_f32_16x16x32_bf16 v[6:9], v[200:203], v[192:195], v[6:9]
	v_mfma_f32_16x16x32_bf16 v[2:5], v[208:211], v[192:195], v[2:5]
	s_cbranch_scc1 .Lkdone_sb
	s_barrier
	s_branch .LBB0_897

; #define G_STAGE(bufoff, gbase, voff) do { _Pragma("unroll") for (int _i = 0; _i < 2; ++_i) \
;         __builtin_amdgcn_global_load_lds((const unsigned*)((const char*)(gbase) + (voff)[_i]), (LAS unsigned*)(lds + (bufoff) + ldsw + _i * 8192), 16, 0, 0); } while (0)
; #define G_WAIT_V(n) asm volatile("s_waitcnt vmcnt(" #n ")" ::: "memory")
; #define G_WAIT_L(n) asm volatile("s_waitcnt lgkmcnt(" #n ")" ::: "memory")
; #define G_BAR __builtin_amdgcn_s_barrier()
; #define G_SCHED __builtin_amdgcn_sched_barrier(0)
; template <int MODE  , class Epi, class Sched>
; __device__ __forceinline__ void gemm_phase(LAS unsigned char* lds, const GemmDesc g, const Sched& S, const Epi& E) {
;     ...
;             G_LDB(B0, 0, 0); G_SCHED; G_LDA(At, 0, 0); G_STAGE(G_SA(1, 1), a1 + hstepA, voffA);
;             G_WAIT_L(8); G_BAR; G_WAIT_L(0); G_MMA(0, 0, At, B0); G_BAR; G_SCHED;
;             G_LDB(B1, 0, 1); G_STAGE(G_SB(0, 0), b2, voffB);
;             G_BAR; G_WAIT_L(0); G_MMA(0, 1, At, B1); G_BAR;
;             G_LDA(At, 0, 1); G_STAGE(G_SA(0, 0), a2, voffA);
;             G_BAR; G_WAIT_L(0); G_MMA(1, 0, At, B0); G_BAR; G_SCHED;
;             G_STAGE(G_SB(0, 1), b2 + hstepB, voffB);
;             G_WAIT_V(6); G_BAR; G_MMA(1, 1, At, B1); G_BAR;
.LBB0_987:
	s_add_u32 s34, s20, 0x100
	s_addc_u32 s35, s21, 0
	s_cmp_eq_u32 s60, 12
	s_cselect_b32 s43, s17, s35
	s_cselect_b32 s42, s16, s34
	s_cselect_b32 s41, s3, s59
	s_cselect_b32 s40, s2, s15
	s_add_u32 s98, s20, 0x84080
	s_addc_u32 s99, s21, 0
	s_add_i32 m0, s44, 0xc000
	ds_read_b128 v[162:165], v144
	ds_read_b128 v[166:169], v144 offset:1024
	ds_read_b128 v[170:173], v144 offset:2048
	ds_read_b128 v[174:177], v144 offset:3072
	ds_read_b128 v[178:181], v144 offset:4096
	ds_read_b128 v[182:185], v144 offset:5120
	ds_read_b128 v[186:189], v144 offset:6144
	ds_read_b128 v[192:195], v144 offset:7168
	global_load_lds_dwordx4 v130, s[98:99]
	s_add_i32 m0, s44, 0xe000
	s_nop 0
	global_load_lds_dwordx4 v134, s[98:99]
	s_waitcnt lgkmcnt(8)
	s_barrier
	s_waitcnt lgkmcnt(0)
	v_mfma_f32_16x16x32_bf16 v[126:129], v[232:235], v[162:165], v[126:129]
	v_mfma_f32_16x16x32_bf16 v[122:125], v[240:243], v[162:165], v[122:125]
	v_mfma_f32_16x16x32_bf16 v[118:121], v[232:235], v[170:173], v[118:121]
	v_mfma_f32_16x16x32_bf16 v[114:117], v[240:243], v[170:173], v[114:117]
	v_mfma_f32_16x16x32_bf16 v[110:113], v[232:235], v[178:181], v[110:113]
	v_mfma_f32_16x16x32_bf16 v[106:109], v[240:243], v[178:181], v[106:109]
	v_mfma_f32_16x16x32_bf16 v[102:105], v[232:235], v[186:189], v[102:105]
	v_mfma_f32_16x16x32_bf16 v[98:101], v[240:243], v[186:189], v[98:101]
	v_mfma_f32_16x16x32_bf16 v[126:129], v[236:239], v[166:169], v[126:129]
	v_mfma_f32_16x16x32_bf16 v[122:125], v[244:247], v[166:169], v[122:125]
	v_mfma_f32_16x16x32_bf16 v[118:121], v[236:239], v[174:177], v[118:121]
	v_mfma_f32_16x16x32_bf16 v[114:117], v[244:247], v[174:177], v[114:117]
	v_mfma_f32_16x16x32_bf16 v[110:113], v[236:239], v[182:185], v[110:113]
	v_mfma_f32_16x16x32_bf16 v[106:109], v[244:247], v[182:185], v[106:109]
	v_mfma_f32_16x16x32_bf16 v[102:105], v[236:239], v[192:195], v[102:105]
	v_mfma_f32_16x16x32_bf16 v[98:101], v[244:247], v[192:195], v[98:101]
	s_barrier
	s_add_i32 s0, s50, s31
	v_add_u32_e32 v145, s51, v142
	s_mov_b32 m0, s0
	ds_read_b128 v[196:199], v145
	ds_read_b128 v[200:203], v145 offset:1024
	ds_read_b128 v[204:207], v145 offset:2048
	ds_read_b128 v[208:211], v145 offset:3072
	global_load_lds_dwordx4 v132, s[40:41]
	s_add_i32 m0, s0, 0x2000
	s_nop 0
	global_load_lds_dwordx4 v136, s[40:41]
	s_barrier
	s_waitcnt lgkmcnt(0)
	v_mfma_f32_16x16x32_bf16 v[94:97], v[196:199], v[162:165], v[94:97]
	v_mfma_f32_16x16x32_bf16 v[90:93], v[204:207], v[162:165], v[90:93]
	v_mfma_f32_16x16x32_bf16 v[86:89], v[196:199], v[170:173], v[86:89]
	v_mfma_f32_16x16x32_bf16 v[82:85], v[204:207], v[170:173], v[82:85]
	v_mfma_f32_16x16x32_bf16 v[78:81], v[196:199], v[178:181], v[78:81]
	v_mfma_f32_16x16x32_bf16 v[74:77], v[204:207], v[178:181], v[74:77]
	v_mfma_f32_16x16x32_bf16 v[70:73], v[196:199], v[186:189], v[70:73]
	v_mfma_f32_16x16x32_bf16 v[66:69], v[204:207], v[186:189], v[66:69]
	v_mfma_f32_16x16x32_bf16 v[94:97], v[200:203], v[166:169], v[94:97]
	v_mfma_f32_16x16x32_bf16 v[90:93], v[208:211], v[166:169], v[90:93]
	v_mfma_f32_16x16x32_bf16 v[86:89], v[200:203], v[174:177], v[86:89]
	v_mfma_f32_16x16x32_bf16 v[82:85], v[208:211], v[174:177], v[82:85]
	v_mfma_f32_16x16x32_bf16 v[78:81], v[200:203], v[182:185], v[78:81]
	v_mfma_f32_16x16x32_bf16 v[74:77], v[208:211], v[182:185], v[74:77]
	v_mfma_f32_16x16x32_bf16 v[70:73], v[200:203], v[192:195], v[70:73]
	v_mfma_f32_16x16x32_bf16 v[66:69], v[208:211], v[192:195], v[66:69]
	s_mov_b32 m0, s44
	s_barrier
	ds_read_b128 v[162:165], v144 offset:16384
	ds_read_b128 v[166:169], v144 offset:17408
	ds_read_b128 v[170:173], v144 offset:18432
	ds_read_b128 v[174:177], v144 offset:19456
	ds_read_b128 v[178:181], v144 offset:20480
	ds_read_b128 v[182:185], v144 offset:21504
	ds_read_b128 v[186:189], v144 offset:22528
	ds_read_b128 v[192:195], v144 offset:23552
	global_load_lds_dwordx4 v130, s[42:43]
	s_mov_b32 m0, s45
	s_nop 0
	global_load_lds_dwordx4 v134, s[42:43]
	s_waitcnt vmcnt(10)
	s_barrier
	s_waitcnt lgkmcnt(0)
	v_mfma_f32_16x16x32_bf16 v[62:65], v[232:235], v[162:165], v[62:65]
	v_mfma_f32_16x16x32_bf16 v[58:61], v[240:243], v[162:165], v[58:61]
	v_mfma_f32_16x16x32_bf16 v[54:57], v[232:235], v[170:173], v[54:57]
	v_mfma_f32_16x16x32_bf16 v[50:53], v[240:243], v[170:173], v[50:53]
	v_mfma_f32_16x16x32_bf16 v[46:49], v[232:235], v[178:181], v[46:49]
	v_mfma_f32_16x16x32_bf16 v[42:45], v[240:243], v[178:181], v[42:45]
	v_mfma_f32_16x16x32_bf16 v[38:41], v[232:235], v[186:189], v[38:41]
	v_mfma_f32_16x16x32_bf16 v[34:37], v[240:243], v[186:189], v[34:37]
	v_mfma_f32_16x16x32_bf16 v[62:65], v[236:239], v[166:169], v[62:65]
	v_mfma_f32_16x16x32_bf16 v[58:61], v[244:247], v[166:169], v[58:61]
	v_mfma_f32_16x16x32_bf16 v[54:57], v[236:239], v[174:177], v[54:57]
	v_mfma_f32_16x16x32_bf16 v[50:53], v[244:247], v[174:177], v[50:53]
	v_mfma_f32_16x16x32_bf16 v[46:49], v[236:239], v[182:185], v[46:49]
	v_mfma_f32_16x16x32_bf16 v[42:45], v[244:247], v[182:185], v[42:45]
	v_mfma_f32_16x16x32_bf16 v[38:41], v[236:239], v[192:195], v[38:41]
	v_mfma_f32_16x16x32_bf16 v[34:37], v[244:247], v[192:195], v[34:37]
	s_barrier
	v_add_u32_e32 v145, 0x18000, v142
	ds_read_b128 v[146:149], v145
	ds_read_b128 v[150:153], v145 offset:1024
	ds_read_b128 v[154:157], v145 offset:2048
	ds_read_b128 v[158:161], v145 offset:3072
	s_add_u32 s0, s40, 0x84000
	s_addc_u32 s1, s41, 0
	s_add_i32 s10, s51, s31
	s_mov_b32 m0, s10
	s_nop 0
	global_load_lds_dwordx4 v132, s[0:1]
	s_add_i32 m0, s10, 0x2000
	s_nop 0
	global_load_lds_dwordx4 v136, s[0:1]
	s_waitcnt vmcnt(6)
	s_barrier
; #define G_STAGE(bufoff, gbase, voff) do { _Pragma("unroll") for (int _i = 0; _i < 2; ++_i) \
;         __builtin_amdgcn_global_load_lds((const unsigned*)((const char*)(gbase) + (voff)[_i]), (LAS unsigned*)(lds + (bufoff) + ldsw + _i * 8192), 16, 0, 0); } while (0)
; #define G_WAIT_V(n) asm volatile("s_waitcnt vmcnt(" #n ")" ::: "memory")
; #define G_WAIT_L(n) asm volatile("s_waitcnt lgkmcnt(" #n ")" ::: "memory")
; #define G_BAR __builtin_amdgcn_s_barrier()
; #define G_SCHED __builtin_amdgcn_sched_barrier(0)
; template <int MODE  , class Epi, class Sched>
; __device__ __forceinline__ void gemm_phase(LAS unsigned char* lds, const GemmDesc g, const Sched& S, const Epi& E) {
;     ...
;             G_WAIT_V(6); G_BAR; G_MMA(1, 1, At, B1); G_BAR;
;             G_LDB(B0, 1, 0); G_SCHED; G_LDA(At, 1, 0); G_STAGE(G_SA(0, 1), a2 + hstepA, voffA);
;             G_WAIT_L(8); G_BAR; G_WAIT_L(0); G_MMA(0, 0, At, B0); G_BAR; G_SCHED;
;             G_LDB(B1, 1, 1); G_STAGE(G_SB(1, 0), b3, voffB);
;             G_BAR; G_WAIT_L(0); G_MMA(0, 1, At, B1); G_BAR;
;             G_LDA(At, 1, 1); G_STAGE(G_SA(1, 0), a3, voffA);
;             G_BAR; G_WAIT_L(0); G_MMA(1, 0, At, B0); G_BAR; G_SCHED;
	v_mfma_f32_16x16x32_bf16 v[30:33], v[196:199], v[162:165], v[30:33]
	v_mfma_f32_16x16x32_bf16 v[26:29], v[204:207], v[162:165], v[26:29]
	v_mfma_f32_16x16x32_bf16 v[22:25], v[196:199], v[170:173], v[22:25]
	v_mfma_f32_16x16x32_bf16 v[18:21], v[204:207], v[170:173], v[18:21]
	v_mfma_f32_16x16x32_bf16 v[14:17], v[196:199], v[178:181], v[14:17]
	v_mfma_f32_16x16x32_bf16 v[10:13], v[204:207], v[178:181], v[10:13]
	v_mfma_f32_16x16x32_bf16 v[6:9], v[196:199], v[186:189], v[6:9]
	v_mfma_f32_16x16x32_bf16 v[2:5], v[204:207], v[186:189], v[2:5]
	v_mfma_f32_16x16x32_bf16 v[30:33], v[200:203], v[166:169], v[30:33]
	v_mfma_f32_16x16x32_bf16 v[26:29], v[208:211], v[166:169], v[26:29]
	v_mfma_f32_16x16x32_bf16 v[22:25], v[200:203], v[174:177], v[22:25]
	v_mfma_f32_16x16x32_bf16 v[18:21], v[208:211], v[174:177], v[18:21]
	v_mfma_f32_16x16x32_bf16 v[14:17], v[200:203], v[182:185], v[14:17]
	v_mfma_f32_16x16x32_bf16 v[10:13], v[208:211], v[182:185], v[10:13]
	v_mfma_f32_16x16x32_bf16 v[6:9], v[200:203], v[192:195], v[6:9]
	v_mfma_f32_16x16x32_bf16 v[2:5], v[208:211], v[192:195], v[2:5]
	s_add_i32 s10, 0, 0x18000
	s_barrier
	s_add_u32 s0, s42, 0x84000
	s_addc_u32 s1, s43, 0
	s_mov_b32 m0, s46
	ds_read_b128 v[162:165], v144 offset:32768
	ds_read_b128 v[166:169], v144 offset:33792
	ds_read_b128 v[170:173], v144 offset:34816
	ds_read_b128 v[174:177], v144 offset:35840
	ds_read_b128 v[178:181], v144 offset:36864
	ds_read_b128 v[182:185], v144 offset:37888
	ds_read_b128 v[186:189], v144 offset:38912
	ds_read_b128 v[192:195], v144 offset:39936
	global_load_lds_dwordx4 v130, s[0:1]
	s_mov_b32 m0, s47
	s_nop 0
	global_load_lds_dwordx4 v134, s[0:1]
	s_waitcnt lgkmcnt(8)
	s_barrier
	s_waitcnt lgkmcnt(0)
	v_mfma_f32_16x16x32_bf16 v[126:129], v[146:149], v[162:165], v[126:129]
	v_mfma_f32_16x16x32_bf16 v[122:125], v[154:157], v[162:165], v[122:125]
	v_mfma_f32_16x16x32_bf16 v[118:121], v[146:149], v[170:173], v[118:121]
	v_mfma_f32_16x16x32_bf16 v[114:117], v[154:157], v[170:173], v[114:117]
	v_mfma_f32_16x16x32_bf16 v[110:113], v[146:149], v[178:181], v[110:113]
	v_mfma_f32_16x16x32_bf16 v[106:109], v[154:157], v[178:181], v[106:109]
	v_mfma_f32_16x16x32_bf16 v[102:105], v[146:149], v[186:189], v[102:105]
	v_mfma_f32_16x16x32_bf16 v[98:101], v[154:157], v[186:189], v[98:101]
	v_mfma_f32_16x16x32_bf16 v[126:129], v[150:153], v[166:169], v[126:129]
	v_mfma_f32_16x16x32_bf16 v[122:125], v[158:161], v[166:169], v[122:125]
	v_mfma_f32_16x16x32_bf16 v[118:121], v[150:153], v[174:177], v[118:121]
	v_mfma_f32_16x16x32_bf16 v[114:117], v[158:161], v[174:177], v[114:117]
	v_mfma_f32_16x16x32_bf16 v[110:113], v[150:153], v[182:185], v[110:113]
	v_mfma_f32_16x16x32_bf16 v[106:109], v[158:161], v[182:185], v[106:109]
	v_mfma_f32_16x16x32_bf16 v[102:105], v[150:153], v[192:195], v[102:105]
	v_mfma_f32_16x16x32_bf16 v[98:101], v[158:161], v[192:195], v[98:101]
	s_barrier
	s_add_i32 s11, 0, 0x1c000
	s_add_i32 s0, s10, s31
	v_add_u32_e32 v145, s11, v142
	s_add_u32 s98, s40, 0x80
	s_addc_u32 s99, s41, 0
	s_mov_b32 m0, s0
	ds_read_b128 v[196:199], v145
	ds_read_b128 v[200:203], v145 offset:1024
	ds_read_b128 v[204:207], v145 offset:2048
	ds_read_b128 v[208:211], v145 offset:3072
	global_load_lds_dwordx4 v132, s[98:99]
	s_add_i32 m0, s0, 0x2000
	s_nop 0
	global_load_lds_dwordx4 v136, s[98:99]
	s_barrier
	s_waitcnt lgkmcnt(0)
	v_mfma_f32_16x16x32_bf16 v[94:97], v[196:199], v[162:165], v[94:97]
	v_mfma_f32_16x16x32_bf16 v[90:93], v[204:207], v[162:165], v[90:93]
	v_mfma_f32_16x16x32_bf16 v[86:89], v[196:199], v[170:173], v[86:89]
	v_mfma_f32_16x16x32_bf16 v[82:85], v[204:207], v[170:173], v[82:85]
	v_mfma_f32_16x16x32_bf16 v[78:81], v[196:199], v[178:181], v[78:81]
	v_mfma_f32_16x16x32_bf16 v[74:77], v[204:207], v[178:181], v[74:77]
	v_mfma_f32_16x16x32_bf16 v[70:73], v[196:199], v[186:189], v[70:73]
	v_mfma_f32_16x16x32_bf16 v[66:69], v[204:207], v[186:189], v[66:69]
	v_mfma_f32_16x16x32_bf16 v[94:97], v[200:203], v[166:169], v[94:97]
	v_mfma_f32_16x16x32_bf16 v[90:93], v[208:211], v[166:169], v[90:93]
	v_mfma_f32_16x16x32_bf16 v[86:89], v[200:203], v[174:177], v[86:89]
	v_mfma_f32_16x16x32_bf16 v[82:85], v[208:211], v[174:177], v[82:85]
	v_mfma_f32_16x16x32_bf16 v[78:81], v[200:203], v[182:185], v[78:81]
	v_mfma_f32_16x16x32_bf16 v[74:77], v[208:211], v[182:185], v[74:77]
	v_mfma_f32_16x16x32_bf16 v[70:73], v[200:203], v[192:195], v[70:73]
	v_mfma_f32_16x16x32_bf16 v[66:69], v[208:211], v[192:195], v[66:69]
	s_mov_b32 m0, s48
	s_add_u32 s98, s42, 0x80
	s_addc_u32 s99, s43, 0
	s_barrier
; #define G_STAGE(bufoff, gbase, voff) do { _Pragma("unroll") for (int _i = 0; _i < 2; ++_i) \
;         __builtin_amdgcn_global_load_lds((const unsigned*)((const char*)(gbase) + (voff)[_i]), (LAS unsigned*)(lds + (bufoff) + ldsw + _i * 8192), 16, 0, 0); } while (0)
; #define G_WAIT_V(n) asm volatile("s_waitcnt vmcnt(" #n ")" ::: "memory")
; #define G_WAIT_L(n) asm volatile("s_waitcnt lgkmcnt(" #n ")" ::: "memory")
; #define G_BAR __builtin_amdgcn_s_barrier()
; #define G_SCHED __builtin_amdgcn_sched_barrier(0)
; template <int MODE  , class Epi, class Sched>
; __device__ __forceinline__ void gemm_phase(LAS unsigned char* lds, const GemmDesc g, const Sched& S, const Epi& E) {
;     ...
;             G_LDA(At, 1, 1); G_STAGE(G_SA(1, 0), a3, voffA);
;             G_BAR; G_WAIT_L(0); G_MMA(1, 0, At, B0); G_BAR; G_SCHED;
;             G_STAGE(G_SB(1, 1), b3 + hstepB, voffB);
;             G_WAIT_V(6); G_BAR; G_MMA(1, 1, At, B1); G_BAR;
;         }
	ds_read_b128 v[162:165], v144 offset:49152
	ds_read_b128 v[166:169], v144 offset:50176
	ds_read_b128 v[170:173], v144 offset:51200
	ds_read_b128 v[174:177], v144 offset:52224
	ds_read_b128 v[178:181], v144 offset:53248
	ds_read_b128 v[182:185], v144 offset:54272
	ds_read_b128 v[186:189], v144 offset:55296
	ds_read_b128 v[192:195], v144 offset:56320
	global_load_lds_dwordx4 v130, s[98:99]
	s_mov_b32 m0, s49
	s_nop 0
	global_load_lds_dwordx4 v134, s[98:99]
	s_waitcnt vmcnt(10)
	s_barrier
	s_waitcnt lgkmcnt(0)
	v_mfma_f32_16x16x32_bf16 v[62:65], v[146:149], v[162:165], v[62:65]
	v_mfma_f32_16x16x32_bf16 v[58:61], v[154:157], v[162:165], v[58:61]
	v_mfma_f32_16x16x32_bf16 v[54:57], v[146:149], v[170:173], v[54:57]
	v_mfma_f32_16x16x32_bf16 v[50:53], v[154:157], v[170:173], v[50:53]
	v_mfma_f32_16x16x32_bf16 v[46:49], v[146:149], v[178:181], v[46:49]
	v_mfma_f32_16x16x32_bf16 v[42:45], v[154:157], v[178:181], v[42:45]
	v_mfma_f32_16x16x32_bf16 v[38:41], v[146:149], v[186:189], v[38:41]
	v_mfma_f32_16x16x32_bf16 v[34:37], v[154:157], v[186:189], v[34:37]
	v_mfma_f32_16x16x32_bf16 v[62:65], v[150:153], v[166:169], v[62:65]
	v_mfma_f32_16x16x32_bf16 v[58:61], v[158:161], v[166:169], v[58:61]
	v_mfma_f32_16x16x32_bf16 v[54:57], v[150:153], v[174:177], v[54:57]
	v_mfma_f32_16x16x32_bf16 v[50:53], v[158:161], v[174:177], v[50:53]
	v_mfma_f32_16x16x32_bf16 v[46:49], v[150:153], v[182:185], v[46:49]
	v_mfma_f32_16x16x32_bf16 v[42:45], v[158:161], v[182:185], v[42:45]
	v_mfma_f32_16x16x32_bf16 v[38:41], v[150:153], v[192:195], v[38:41]
	v_mfma_f32_16x16x32_bf16 v[34:37], v[158:161], v[192:195], v[34:37]
	s_barrier
	v_add_u32_e32 v145, s50, v142
	ds_read_b128 v[232:235], v145
	ds_read_b128 v[236:239], v145 offset:1024
	ds_read_b128 v[240:243], v145 offset:2048
	ds_read_b128 v[244:247], v145 offset:3072
	s_add_u32 s0, s40, 0x84080
	s_addc_u32 s1, s41, 0
	s_add_i32 s10, s11, s31
	s_mov_b32 m0, s10
	s_nop 0
	global_load_lds_dwordx4 v132, s[0:1]
	s_add_i32 m0, s10, 0x2000
	s_nop 0
	global_load_lds_dwordx4 v136, s[0:1]
	s_waitcnt vmcnt(6)
	s_barrier
	v_mfma_f32_16x16x32_bf16 v[30:33], v[196:199], v[162:165], v[30:33]
	s_add_i32 s60, s60, 2
	s_add_u32 s15, s15, 0x100
	s_addc_u32 s59, s59, 0
	s_cmp_gt_u32 s60, 13
	s_mov_b64 s[20:21], s[34:35]
	v_mfma_f32_16x16x32_bf16 v[26:29], v[204:207], v[162:165], v[26:29]
	v_mfma_f32_16x16x32_bf16 v[22:25], v[196:199], v[170:173], v[22:25]
	v_mfma_f32_16x16x32_bf16 v[18:21], v[204:207], v[170:173], v[18:21]
	v_mfma_f32_16x16x32_bf16 v[14:17], v[196:199], v[178:181], v[14:17]
	v_mfma_f32_16x16x32_bf16 v[10:13], v[204:207], v[178:181], v[10:13]
	v_mfma_f32_16x16x32_bf16 v[6:9], v[196:199], v[186:189], v[6:9]
	v_mfma_f32_16x16x32_bf16 v[2:5], v[204:207], v[186:189], v[2:5]
	v_mfma_f32_16x16x32_bf16 v[30:33], v[200:203], v[166:169], v[30:33]
	v_mfma_f32_16x16x32_bf16 v[26:29], v[208:211], v[166:169], v[26:29]
	v_mfma_f32_16x16x32_bf16 v[22:25], v[200:203], v[174:177], v[22:25]
	v_mfma_f32_16x16x32_bf16 v[18:21], v[208:211], v[174:177], v[18:21]
	v_mfma_f32_16x16x32_bf16 v[14:17], v[200:203], v[182:185], v[14:17]
	v_mfma_f32_16x16x32_bf16 v[10:13], v[208:211], v[182:185], v[10:13]
	v_mfma_f32_16x16x32_bf16 v[6:9], v[200:203], v[192:195], v[6:9]
	v_mfma_f32_16x16x32_bf16 v[2:5], v[208:211], v[192:195], v[2:5]
	s_cbranch_scc1 .Lkdone_sc
	s_barrier
	s_branch .LBB0_987

; #define G_STAGE(bufoff, gbase, voff) do { _Pragma("unroll") for (int _i = 0; _i < 2; ++_i) \
;         __builtin_amdgcn_global_load_lds((const unsigned*)((const char*)(gbase) + (voff)[_i]), (LAS unsigned*)(lds + (bufoff) + ldsw + _i * 8192), 16, 0, 0); } while (0)
; #define G_WAIT_V(n) asm volatile("s_waitcnt vmcnt(" #n ")" ::: "memory")
; #define G_WAIT_L(n) asm volatile("s_waitcnt lgkmcnt(" #n ")" ::: "memory")
; #define G_BAR __builtin_amdgcn_s_barrier()
; #define G_SCHED __builtin_amdgcn_sched_barrier(0)
; template <int MODE  , class Epi, class Sched>
; __device__ __forceinline__ void gemm_phase(LAS unsigned char* lds, const GemmDesc g, const Sched& S, const Epi& E) {
;     ...
;             G_LDB(B0, 0, 0); G_SCHED; G_LDA(At, 0, 0); G_STAGE(G_SA(1, 1), a1 + hstepA, voffA);
;             G_WAIT_L(8); G_BAR; G_WAIT_L(0); G_MMA(0, 0, At, B0); G_BAR; G_SCHED;
;             G_LDB(B1, 0, 1); G_STAGE(G_SB(0, 0), b2, voffB);
;             G_BAR; G_WAIT_L(0); G_MMA(0, 1, At, B1); G_BAR;
;             G_LDA(At, 0, 1); G_STAGE(G_SA(0, 0), a2, voffA);
;             G_BAR; G_WAIT_L(0); G_MMA(1, 0, At, B0); G_BAR; G_SCHED;
;             G_STAGE(G_SB(0, 1), b2 + hstepB, voffB);
;             G_WAIT_V(6); G_BAR; G_MMA(1, 1, At, B1); G_BAR;
.LBB0_1017:
	s_add_u32 s4, s2, 0x100
	s_addc_u32 s5, s3, 0
	s_cmp_eq_u32 s87, 28
	s_cselect_b32 s53, s47, s5
	s_cselect_b32 s52, s46, s4
	s_cselect_b32 s51, s49, s86
	s_cselect_b32 s50, s48, s85
	s_add_u32 s98, s2, 0x84080
	s_addc_u32 s99, s3, 0
	s_add_i32 m0, s58, 0xc000
	ds_read_b128 v[174:177], v164
	ds_read_b128 v[178:181], v164 offset:1024
	ds_read_b128 v[182:185], v164 offset:2048
	ds_read_b128 v[186:189], v164 offset:3072
	ds_read_b128 v[192:195], v164 offset:4096
	ds_read_b128 v[196:199], v164 offset:5120
	ds_read_b128 v[200:203], v164 offset:6144
	ds_read_b128 v[204:207], v164 offset:7168
	global_load_lds_dwordx4 v138, s[98:99]
	s_add_i32 m0, s58, 0xe000
	s_nop 0
	global_load_lds_dwordx4 v142, s[98:99]
	s_waitcnt lgkmcnt(8)
	s_barrier
	s_waitcnt lgkmcnt(0)
	v_mfma_f32_16x16x32_bf16 v[126:129], v[232:235], v[174:177], v[126:129]
	v_mfma_f32_16x16x32_bf16 v[122:125], v[240:243], v[174:177], v[122:125]
	v_mfma_f32_16x16x32_bf16 v[110:113], v[232:235], v[182:185], v[110:113]
	v_mfma_f32_16x16x32_bf16 v[106:109], v[240:243], v[182:185], v[106:109]
	v_mfma_f32_16x16x32_bf16 v[94:97], v[232:235], v[192:195], v[94:97]
	v_mfma_f32_16x16x32_bf16 v[90:93], v[240:243], v[192:195], v[90:93]
	v_mfma_f32_16x16x32_bf16 v[78:81], v[232:235], v[200:203], v[78:81]
	v_mfma_f32_16x16x32_bf16 v[74:77], v[240:243], v[200:203], v[74:77]
	v_mfma_f32_16x16x32_bf16 v[126:129], v[236:239], v[178:181], v[126:129]
	v_mfma_f32_16x16x32_bf16 v[122:125], v[244:247], v[178:181], v[122:125]
	v_mfma_f32_16x16x32_bf16 v[110:113], v[236:239], v[186:189], v[110:113]
	v_mfma_f32_16x16x32_bf16 v[106:109], v[244:247], v[186:189], v[106:109]
	v_mfma_f32_16x16x32_bf16 v[94:97], v[236:239], v[196:199], v[94:97]
	v_mfma_f32_16x16x32_bf16 v[90:93], v[244:247], v[196:199], v[90:93]
	v_mfma_f32_16x16x32_bf16 v[78:81], v[236:239], v[204:207], v[78:81]
	v_mfma_f32_16x16x32_bf16 v[74:77], v[244:247], v[204:207], v[74:77]
	s_barrier
	s_add_i32 s0, s66, s57
	s_mov_b32 m0, s0
	ds_read_b128 v[208:211], v165
	ds_read_b128 v[212:215], v165 offset:1024
	ds_read_b128 v[216:219], v165 offset:2048
	ds_read_b128 v[220:223], v165 offset:3072
	global_load_lds_dwordx4 v140, s[50:51]
	s_add_i32 m0, s0, 0x2000
	s_nop 0
	global_load_lds_dwordx4 v144, s[50:51]
	s_barrier
	s_waitcnt lgkmcnt(0)
	v_mfma_f32_16x16x32_bf16 v[118:121], v[208:211], v[174:177], v[118:121]
	v_mfma_f32_16x16x32_bf16 v[114:117], v[216:219], v[174:177], v[114:117]
	v_mfma_f32_16x16x32_bf16 v[102:105], v[208:211], v[182:185], v[102:105]
	v_mfma_f32_16x16x32_bf16 v[98:101], v[216:219], v[182:185], v[98:101]
	v_mfma_f32_16x16x32_bf16 v[86:89], v[208:211], v[192:195], v[86:89]
	v_mfma_f32_16x16x32_bf16 v[82:85], v[216:219], v[192:195], v[82:85]
	v_mfma_f32_16x16x32_bf16 v[70:73], v[208:211], v[200:203], v[70:73]
	v_mfma_f32_16x16x32_bf16 v[66:69], v[216:219], v[200:203], v[66:69]
	v_mfma_f32_16x16x32_bf16 v[118:121], v[212:215], v[178:181], v[118:121]
	v_mfma_f32_16x16x32_bf16 v[114:117], v[220:223], v[178:181], v[114:117]
	v_mfma_f32_16x16x32_bf16 v[102:105], v[212:215], v[186:189], v[102:105]
	v_mfma_f32_16x16x32_bf16 v[98:101], v[220:223], v[186:189], v[98:101]
	v_mfma_f32_16x16x32_bf16 v[86:89], v[212:215], v[196:199], v[86:89]
	v_mfma_f32_16x16x32_bf16 v[82:85], v[220:223], v[196:199], v[82:85]
	v_mfma_f32_16x16x32_bf16 v[70:73], v[212:215], v[204:207], v[70:73]
	v_mfma_f32_16x16x32_bf16 v[66:69], v[220:223], v[204:207], v[66:69]
	s_mov_b32 m0, s58
	s_barrier
	ds_read_b128 v[174:177], v164 offset:16384
	ds_read_b128 v[178:181], v164 offset:17408
	ds_read_b128 v[182:185], v164 offset:18432
	ds_read_b128 v[186:189], v164 offset:19456
	ds_read_b128 v[192:195], v164 offset:20480
	ds_read_b128 v[196:199], v164 offset:21504
	ds_read_b128 v[200:203], v164 offset:22528
	ds_read_b128 v[204:207], v164 offset:23552
	global_load_lds_dwordx4 v138, s[52:53]
	s_mov_b32 m0, s59
	s_nop 0
	global_load_lds_dwordx4 v142, s[52:53]
	s_waitcnt vmcnt(10)
	s_barrier
	s_waitcnt lgkmcnt(0)
	v_mfma_f32_16x16x32_bf16 v[62:65], v[232:235], v[174:177], v[62:65]
	v_mfma_f32_16x16x32_bf16 v[58:61], v[240:243], v[174:177], v[58:61]
	v_mfma_f32_16x16x32_bf16 v[46:49], v[232:235], v[182:185], v[46:49]
	v_mfma_f32_16x16x32_bf16 v[42:45], v[240:243], v[182:185], v[42:45]
	v_mfma_f32_16x16x32_bf16 v[30:33], v[232:235], v[192:195], v[30:33]
	v_mfma_f32_16x16x32_bf16 v[26:29], v[240:243], v[192:195], v[26:29]
	v_mfma_f32_16x16x32_bf16 v[14:17], v[232:235], v[200:203], v[14:17]
	v_mfma_f32_16x16x32_bf16 v[10:13], v[240:243], v[200:203], v[10:13]
	v_mfma_f32_16x16x32_bf16 v[62:65], v[236:239], v[178:181], v[62:65]
	v_mfma_f32_16x16x32_bf16 v[58:61], v[244:247], v[178:181], v[58:61]
	v_mfma_f32_16x16x32_bf16 v[46:49], v[236:239], v[186:189], v[46:49]
	v_mfma_f32_16x16x32_bf16 v[42:45], v[244:247], v[186:189], v[42:45]
	v_mfma_f32_16x16x32_bf16 v[30:33], v[236:239], v[196:199], v[30:33]
	v_mfma_f32_16x16x32_bf16 v[26:29], v[244:247], v[196:199], v[26:29]
	v_mfma_f32_16x16x32_bf16 v[14:17], v[236:239], v[204:207], v[14:17]
	v_mfma_f32_16x16x32_bf16 v[10:13], v[244:247], v[204:207], v[10:13]
	s_barrier
	v_add_u32_e32 v146, 0x18000, v160
	ds_read_b128 v[130:133], v146
	ds_read_b128 v[134:137], v146 offset:1024
	ds_read_b128 v[154:157], v146 offset:2048
	ds_read_b128 v[170:173], v146 offset:3072
	s_add_u32 s0, s50, 0x84000
	s_addc_u32 s1, s51, 0
	s_add_i32 s2, s67, s57
	s_mov_b32 m0, s2
	s_nop 0
	global_load_lds_dwordx4 v140, s[0:1]
	s_add_i32 m0, s2, 0x2000
	s_nop 0
	global_load_lds_dwordx4 v144, s[0:1]
	s_waitcnt vmcnt(6)
	s_barrier
; #define G_STAGE(bufoff, gbase, voff) do { _Pragma("unroll") for (int _i = 0; _i < 2; ++_i) \
;         __builtin_amdgcn_global_load_lds((const unsigned*)((const char*)(gbase) + (voff)[_i]), (LAS unsigned*)(lds + (bufoff) + ldsw + _i * 8192), 16, 0, 0); } while (0)
; #define G_WAIT_V(n) asm volatile("s_waitcnt vmcnt(" #n ")" ::: "memory")
; #define G_WAIT_L(n) asm volatile("s_waitcnt lgkmcnt(" #n ")" ::: "memory")
; #define G_BAR __builtin_amdgcn_s_barrier()
; #define G_SCHED __builtin_amdgcn_sched_barrier(0)
; template <int MODE  , class Epi, class Sched>
; __device__ __forceinline__ void gemm_phase(LAS unsigned char* lds, const GemmDesc g, const Sched& S, const Epi& E) {
;     ...
;             G_WAIT_V(6); G_BAR; G_MMA(1, 1, At, B1); G_BAR;
;             G_LDB(B0, 1, 0); G_SCHED; G_LDA(At, 1, 0); G_STAGE(G_SA(0, 1), a2 + hstepA, voffA);
;             G_WAIT_L(8); G_BAR; G_WAIT_L(0); G_MMA(0, 0, At, B0); G_BAR; G_SCHED;
;             G_LDB(B1, 1, 1); G_STAGE(G_SB(1, 0), b3, voffB);
;             G_BAR; G_WAIT_L(0); G_MMA(0, 1, At, B1); G_BAR;
;             G_LDA(At, 1, 1); G_STAGE(G_SA(1, 0), a3, voffA);
;             G_BAR; G_WAIT_L(0); G_MMA(1, 0, At, B0); G_BAR; G_SCHED;
	v_mfma_f32_16x16x32_bf16 v[54:57], v[208:211], v[174:177], v[54:57]
	v_mfma_f32_16x16x32_bf16 v[50:53], v[216:219], v[174:177], v[50:53]
	v_mfma_f32_16x16x32_bf16 v[38:41], v[208:211], v[182:185], v[38:41]
	v_mfma_f32_16x16x32_bf16 v[34:37], v[216:219], v[182:185], v[34:37]
	v_mfma_f32_16x16x32_bf16 v[22:25], v[208:211], v[192:195], v[22:25]
	v_mfma_f32_16x16x32_bf16 v[18:21], v[216:219], v[192:195], v[18:21]
	v_mfma_f32_16x16x32_bf16 v[6:9], v[208:211], v[200:203], v[6:9]
	v_mfma_f32_16x16x32_bf16 v[2:5], v[216:219], v[200:203], v[2:5]
	v_mfma_f32_16x16x32_bf16 v[54:57], v[212:215], v[178:181], v[54:57]
	v_mfma_f32_16x16x32_bf16 v[50:53], v[220:223], v[178:181], v[50:53]
	v_mfma_f32_16x16x32_bf16 v[38:41], v[212:215], v[186:189], v[38:41]
	v_mfma_f32_16x16x32_bf16 v[34:37], v[220:223], v[186:189], v[34:37]
	v_mfma_f32_16x16x32_bf16 v[22:25], v[212:215], v[196:199], v[22:25]
	v_mfma_f32_16x16x32_bf16 v[18:21], v[220:223], v[196:199], v[18:21]
	v_mfma_f32_16x16x32_bf16 v[6:9], v[212:215], v[204:207], v[6:9]
	v_mfma_f32_16x16x32_bf16 v[2:5], v[220:223], v[204:207], v[2:5]
	s_add_i32 s2, 0, 0x18000
	s_barrier
	s_add_u32 s0, s52, 0x84000
	s_addc_u32 s1, s53, 0
	s_mov_b32 m0, s60
	ds_read_b128 v[174:177], v164 offset:32768
	ds_read_b128 v[178:181], v164 offset:33792
	ds_read_b128 v[182:185], v164 offset:34816
	ds_read_b128 v[186:189], v164 offset:35840
	ds_read_b128 v[192:195], v164 offset:36864
	ds_read_b128 v[196:199], v164 offset:37888
	ds_read_b128 v[200:203], v164 offset:38912
	ds_read_b128 v[204:207], v164 offset:39936
	global_load_lds_dwordx4 v138, s[0:1]
	s_mov_b32 m0, s61
	s_nop 0
	global_load_lds_dwordx4 v142, s[0:1]
	s_waitcnt lgkmcnt(8)
	s_barrier
	s_waitcnt lgkmcnt(0)
	v_mfma_f32_16x16x32_bf16 v[126:129], v[130:133], v[174:177], v[126:129]
	v_mfma_f32_16x16x32_bf16 v[122:125], v[154:157], v[174:177], v[122:125]
	v_mfma_f32_16x16x32_bf16 v[110:113], v[130:133], v[182:185], v[110:113]
	v_mfma_f32_16x16x32_bf16 v[106:109], v[154:157], v[182:185], v[106:109]
	v_mfma_f32_16x16x32_bf16 v[94:97], v[130:133], v[192:195], v[94:97]
	v_mfma_f32_16x16x32_bf16 v[90:93], v[154:157], v[192:195], v[90:93]
	v_mfma_f32_16x16x32_bf16 v[78:81], v[130:133], v[200:203], v[78:81]
	v_mfma_f32_16x16x32_bf16 v[74:77], v[154:157], v[200:203], v[74:77]
	v_mfma_f32_16x16x32_bf16 v[126:129], v[134:137], v[178:181], v[126:129]
	v_mfma_f32_16x16x32_bf16 v[122:125], v[170:173], v[178:181], v[122:125]
	v_mfma_f32_16x16x32_bf16 v[110:113], v[134:137], v[186:189], v[110:113]
	v_mfma_f32_16x16x32_bf16 v[106:109], v[170:173], v[186:189], v[106:109]
	v_mfma_f32_16x16x32_bf16 v[94:97], v[134:137], v[196:199], v[94:97]
	v_mfma_f32_16x16x32_bf16 v[90:93], v[170:173], v[196:199], v[90:93]
	v_mfma_f32_16x16x32_bf16 v[78:81], v[134:137], v[204:207], v[78:81]
	v_mfma_f32_16x16x32_bf16 v[74:77], v[170:173], v[204:207], v[74:77]
	s_barrier
	s_add_i32 s3, 0, 0x1c000
	s_add_i32 s0, s2, s57
	v_add_u32_e32 v146, s3, v160
	s_add_u32 s98, s50, 0x80
	s_addc_u32 s99, s51, 0
	s_mov_b32 m0, s0
	ds_read_b128 v[208:211], v146
	ds_read_b128 v[212:215], v146 offset:1024
	ds_read_b128 v[216:219], v146 offset:2048
	ds_read_b128 v[220:223], v146 offset:3072
	global_load_lds_dwordx4 v140, s[98:99]
	s_add_i32 m0, s0, 0x2000
	s_nop 0
	global_load_lds_dwordx4 v144, s[98:99]
	s_barrier
	s_waitcnt lgkmcnt(0)
	v_mfma_f32_16x16x32_bf16 v[118:121], v[208:211], v[174:177], v[118:121]
	v_mfma_f32_16x16x32_bf16 v[114:117], v[216:219], v[174:177], v[114:117]
	v_mfma_f32_16x16x32_bf16 v[102:105], v[208:211], v[182:185], v[102:105]
	v_mfma_f32_16x16x32_bf16 v[98:101], v[216:219], v[182:185], v[98:101]
	v_mfma_f32_16x16x32_bf16 v[86:89], v[208:211], v[192:195], v[86:89]
	v_mfma_f32_16x16x32_bf16 v[82:85], v[216:219], v[192:195], v[82:85]
	v_mfma_f32_16x16x32_bf16 v[70:73], v[208:211], v[200:203], v[70:73]
	v_mfma_f32_16x16x32_bf16 v[66:69], v[216:219], v[200:203], v[66:69]
	v_mfma_f32_16x16x32_bf16 v[118:121], v[212:215], v[178:181], v[118:121]
	v_mfma_f32_16x16x32_bf16 v[114:117], v[220:223], v[178:181], v[114:117]
	v_mfma_f32_16x16x32_bf16 v[102:105], v[212:215], v[186:189], v[102:105]
	v_mfma_f32_16x16x32_bf16 v[98:101], v[220:223], v[186:189], v[98:101]
	v_mfma_f32_16x16x32_bf16 v[86:89], v[212:215], v[196:199], v[86:89]
	v_mfma_f32_16x16x32_bf16 v[82:85], v[220:223], v[196:199], v[82:85]
	v_mfma_f32_16x16x32_bf16 v[70:73], v[212:215], v[204:207], v[70:73]
	v_mfma_f32_16x16x32_bf16 v[66:69], v[220:223], v[204:207], v[66:69]
	s_mov_b32 m0, s64
	s_add_u32 s98, s52, 0x80
	s_addc_u32 s99, s53, 0
	s_barrier
; #define G_STAGE(bufoff, gbase, voff) do { _Pragma("unroll") for (int _i = 0; _i < 2; ++_i) \
;         __builtin_amdgcn_global_load_lds((const unsigned*)((const char*)(gbase) + (voff)[_i]), (LAS unsigned*)(lds + (bufoff) + ldsw + _i * 8192), 16, 0, 0); } while (0)
; #define G_WAIT_V(n) asm volatile("s_waitcnt vmcnt(" #n ")" ::: "memory")
; #define G_WAIT_L(n) asm volatile("s_waitcnt lgkmcnt(" #n ")" ::: "memory")
; #define G_BAR __builtin_amdgcn_s_barrier()
; #define G_SCHED __builtin_amdgcn_sched_barrier(0)
; template <int MODE  , class Epi, class Sched>
; __device__ __forceinline__ void gemm_phase(LAS unsigned char* lds, const GemmDesc g, const Sched& S, const Epi& E) {
;     ...
;             G_LDA(At, 1, 1); G_STAGE(G_SA(1, 0), a3, voffA);
;             G_BAR; G_WAIT_L(0); G_MMA(1, 0, At, B0); G_BAR; G_SCHED;
;             G_STAGE(G_SB(1, 1), b3 + hstepB, voffB);
;             G_WAIT_V(6); G_BAR; G_MMA(1, 1, At, B1); G_BAR;
;         }
	ds_read_b128 v[174:177], v164 offset:49152
	ds_read_b128 v[178:181], v164 offset:50176
	ds_read_b128 v[182:185], v164 offset:51200
	ds_read_b128 v[186:189], v164 offset:52224
	ds_read_b128 v[192:195], v164 offset:53248
	ds_read_b128 v[196:199], v164 offset:54272
	ds_read_b128 v[200:203], v164 offset:55296
	ds_read_b128 v[204:207], v164 offset:56320
	global_load_lds_dwordx4 v138, s[98:99]
	s_mov_b32 m0, s65
	s_nop 0
	global_load_lds_dwordx4 v142, s[98:99]
	s_waitcnt vmcnt(10)
	s_barrier
	s_waitcnt lgkmcnt(0)
	v_mfma_f32_16x16x32_bf16 v[62:65], v[130:133], v[174:177], v[62:65]
	v_mfma_f32_16x16x32_bf16 v[58:61], v[154:157], v[174:177], v[58:61]
	v_mfma_f32_16x16x32_bf16 v[46:49], v[130:133], v[182:185], v[46:49]
	v_mfma_f32_16x16x32_bf16 v[42:45], v[154:157], v[182:185], v[42:45]
	v_mfma_f32_16x16x32_bf16 v[30:33], v[130:133], v[192:195], v[30:33]
	v_mfma_f32_16x16x32_bf16 v[26:29], v[154:157], v[192:195], v[26:29]
	v_mfma_f32_16x16x32_bf16 v[14:17], v[130:133], v[200:203], v[14:17]
	v_mfma_f32_16x16x32_bf16 v[10:13], v[154:157], v[200:203], v[10:13]
	v_mfma_f32_16x16x32_bf16 v[62:65], v[134:137], v[178:181], v[62:65]
	v_mfma_f32_16x16x32_bf16 v[58:61], v[170:173], v[178:181], v[58:61]
	v_mfma_f32_16x16x32_bf16 v[46:49], v[134:137], v[186:189], v[46:49]
	v_mfma_f32_16x16x32_bf16 v[42:45], v[170:173], v[186:189], v[42:45]
	v_mfma_f32_16x16x32_bf16 v[30:33], v[134:137], v[196:199], v[30:33]
	v_mfma_f32_16x16x32_bf16 v[26:29], v[170:173], v[196:199], v[26:29]
	v_mfma_f32_16x16x32_bf16 v[14:17], v[134:137], v[204:207], v[14:17]
	v_mfma_f32_16x16x32_bf16 v[10:13], v[170:173], v[204:207], v[10:13]
	s_barrier
	ds_read_b128 v[232:235], v163
	ds_read_b128 v[236:239], v163 offset:1024
	ds_read_b128 v[240:243], v163 offset:2048
	ds_read_b128 v[244:247], v163 offset:3072
	s_add_u32 s0, s50, 0x84080
	s_addc_u32 s1, s51, 0
	s_add_i32 s2, s3, s57
	s_mov_b32 m0, s2
	s_nop 0
	global_load_lds_dwordx4 v140, s[0:1]
	s_add_i32 m0, s2, 0x2000
	s_nop 0
	global_load_lds_dwordx4 v144, s[0:1]
	s_waitcnt vmcnt(6)
	s_barrier
	v_mfma_f32_16x16x32_bf16 v[54:57], v[208:211], v[174:177], v[54:57]
	s_add_i32 s87, s87, 2
	s_add_u32 s85, s85, 0x100
	s_addc_u32 s86, s86, 0
	s_cmp_gt_u32 s87, 29
	s_mov_b64 s[2:3], s[4:5]
	v_mfma_f32_16x16x32_bf16 v[50:53], v[216:219], v[174:177], v[50:53]
	v_mfma_f32_16x16x32_bf16 v[38:41], v[208:211], v[182:185], v[38:41]
	v_mfma_f32_16x16x32_bf16 v[34:37], v[216:219], v[182:185], v[34:37]
	v_mfma_f32_16x16x32_bf16 v[22:25], v[208:211], v[192:195], v[22:25]
	v_mfma_f32_16x16x32_bf16 v[18:21], v[216:219], v[192:195], v[18:21]
	v_mfma_f32_16x16x32_bf16 v[6:9], v[208:211], v[200:203], v[6:9]
	v_mfma_f32_16x16x32_bf16 v[2:5], v[216:219], v[200:203], v[2:5]
	v_mfma_f32_16x16x32_bf16 v[54:57], v[212:215], v[178:181], v[54:57]
	v_mfma_f32_16x16x32_bf16 v[50:53], v[220:223], v[178:181], v[50:53]
	v_mfma_f32_16x16x32_bf16 v[38:41], v[212:215], v[186:189], v[38:41]
	v_mfma_f32_16x16x32_bf16 v[34:37], v[220:223], v[186:189], v[34:37]
	v_mfma_f32_16x16x32_bf16 v[22:25], v[212:215], v[196:199], v[22:25]
	v_mfma_f32_16x16x32_bf16 v[18:21], v[220:223], v[196:199], v[18:21]
	v_mfma_f32_16x16x32_bf16 v[6:9], v[212:215], v[204:207], v[6:9]
	v_mfma_f32_16x16x32_bf16 v[2:5], v[220:223], v[204:207], v[2:5]
	s_cbranch_scc1 .Lkdone_s1a
	s_barrier
	s_branch .LBB0_1017
